# loop-alignment pinning: explicit s_nop pads place the P1/P7b GEMM K-loops at their fastest 64-byte phase; shorter gelu select
# speedup vs baseline: 1.0089x; 1.0089x over previous
.LBB0_161:
	s_ashr_i32 s55, s54, 31
	s_lshl_b64 s[46:47], s[54:55], 19
	s_add_u32 s14, s85, s46
	s_addc_u32 s15, s86, s47
	s_and_b64 s[46:47], s[40:41], exec
	s_cselect_b32 s55, s15, s43
	s_cselect_b32 s62, s14, s42
	s_ashr_i32 s53, s52, 31
	s_lshl_b64 s[46:47], s[52:53], 19
	s_add_u32 s58, s82, s46
	s_addc_u32 s59, s83, s47
	s_and_b64 s[46:47], s[40:41], exec
	s_cselect_b32 s53, s59, s45
	s_cselect_b32 s63, s58, s44
	s_add_u32 s42, s42, 0x40080
	s_addc_u32 s43, s43, 0
	s_add_u32 s65, s44, 0x100
	v_mov_b32_e32 v0, 0
	s_addc_u32 s66, s45, 0
	s_mov_b32 s67, -2
	v_mov_b32_e32 v1, v0
	v_mov_b32_e32 v2, v0
	v_mov_b32_e32 v3, v0
	v_mov_b32_e32 v4, v0
	v_mov_b32_e32 v5, v0
	v_mov_b32_e32 v6, v0
	v_mov_b32_e32 v7, v0
	v_mov_b32_e32 v48, v0
	v_mov_b32_e32 v49, v0
	v_mov_b32_e32 v50, v0
	v_mov_b32_e32 v51, v0
	v_mov_b32_e32 v52, v0
	v_mov_b32_e32 v53, v0
	v_mov_b32_e32 v54, v0
	v_mov_b32_e32 v55, v0
	s_waitcnt vmcnt(0)
	v_mov_b32_e32 v64, v0
	v_mov_b32_e32 v65, v0
	v_mov_b32_e32 v66, v0
	v_mov_b32_e32 v67, v0
	v_mov_b32_e32 v68, v0
	v_mov_b32_e32 v69, v0
	v_mov_b32_e32 v70, v0
	v_mov_b32_e32 v71, v0
	v_mov_b32_e32 v80, v0
	v_mov_b32_e32 v81, v0
	v_mov_b32_e32 v82, v0
	v_mov_b32_e32 v83, v0
	v_mov_b32_e32 v84, v0
	v_mov_b32_e32 v85, v0
	v_mov_b32_e32 v86, v0
	v_mov_b32_e32 v87, v0
	v_mov_b32_e32 v8, v0
	v_mov_b32_e32 v9, v0
	v_mov_b32_e32 v10, v0
	v_mov_b32_e32 v11, v0
	v_mov_b32_e32 v12, v0
	v_mov_b32_e32 v13, v0
	v_mov_b32_e32 v14, v0
	v_mov_b32_e32 v15, v0
	v_mov_b32_e32 v56, v0
	v_mov_b32_e32 v57, v0
	v_mov_b32_e32 v58, v0
	v_mov_b32_e32 v59, v0
	v_mov_b32_e32 v60, v0
	v_mov_b32_e32 v61, v0
	v_mov_b32_e32 v62, v0
	v_mov_b32_e32 v63, v0
	v_mov_b32_e32 v72, v0
	v_mov_b32_e32 v73, v0
	v_mov_b32_e32 v74, v0
	v_mov_b32_e32 v75, v0
	v_mov_b32_e32 v76, v0
	v_mov_b32_e32 v77, v0
	v_mov_b32_e32 v78, v0
	v_mov_b32_e32 v79, v0
	v_mov_b32_e32 v88, v0
	v_mov_b32_e32 v89, v0
	v_mov_b32_e32 v90, v0
	v_mov_b32_e32 v91, v0
	v_mov_b32_e32 v92, v0
	v_mov_b32_e32 v93, v0
	v_mov_b32_e32 v94, v0
	v_mov_b32_e32 v95, v0
	v_mov_b32_e32 v96, v0
	v_mov_b32_e32 v97, v0
	v_mov_b32_e32 v98, v0
	v_mov_b32_e32 v99, v0
	v_mov_b32_e32 v100, v0
	v_mov_b32_e32 v101, v0
	v_mov_b32_e32 v102, v0
	v_mov_b32_e32 v103, v0
	v_mov_b32_e32 v112, v0
	v_mov_b32_e32 v113, v0
	v_mov_b32_e32 v114, v0
	v_mov_b32_e32 v115, v0
	v_mov_b32_e32 v116, v0
	v_mov_b32_e32 v117, v0
	v_mov_b32_e32 v118, v0
	v_mov_b32_e32 v119, v0
	v_mov_b32_e32 v128, v0
	v_mov_b32_e32 v129, v0
	v_mov_b32_e32 v130, v0
	v_mov_b32_e32 v131, v0
	v_mov_b32_e32 v132, v0
	v_mov_b32_e32 v133, v0
	v_mov_b32_e32 v134, v0
	v_mov_b32_e32 v135, v0
	v_mov_b32_e32 v152, v0
	v_mov_b32_e32 v153, v0
	v_mov_b32_e32 v154, v0
	v_mov_b32_e32 v155, v0
	v_mov_b32_e32 v144, v0
	v_mov_b32_e32 v145, v0
	v_mov_b32_e32 v146, v0
	v_mov_b32_e32 v147, v0
	v_mov_b32_e32 v104, v0
	v_mov_b32_e32 v105, v0
	v_mov_b32_e32 v106, v0
	v_mov_b32_e32 v107, v0
	v_mov_b32_e32 v108, v0
	v_mov_b32_e32 v109, v0
	v_mov_b32_e32 v110, v0
	v_mov_b32_e32 v111, v0
	v_mov_b32_e32 v120, v0
	v_mov_b32_e32 v121, v0
	v_mov_b32_e32 v122, v0
	v_mov_b32_e32 v123, v0
	v_mov_b32_e32 v124, v0
	v_mov_b32_e32 v125, v0
	v_mov_b32_e32 v126, v0
	v_mov_b32_e32 v127, v0
	v_mov_b32_e32 v136, v0
	v_mov_b32_e32 v137, v0
	v_mov_b32_e32 v138, v0
	v_mov_b32_e32 v139, v0
	v_mov_b32_e32 v140, v0
	v_mov_b32_e32 v141, v0
	v_mov_b32_e32 v142, v0
	v_mov_b32_e32 v143, v0
	v_mov_b32_e32 v156, v0
	v_mov_b32_e32 v157, v0
	v_mov_b32_e32 v158, v0
	v_mov_b32_e32 v159, v0
	v_mov_b32_e32 v148, v0
	v_mov_b32_e32 v149, v0
	v_mov_b32_e32 v150, v0
	v_mov_b32_e32 v151, v0
	s_nop 0
	s_nop 0

.LBB0_492:
	v_lshlrev_b32_e32 v224, 1, v222
	v_lshrrev_b32_e32 v18, 1, v221
	v_and_b32_e32 v16, 19, v221
	v_and_b32_e32 v17, 8, v224
	v_and_b32_e32 v18, 4, v18
	v_or3_b32 v16, v16, v17, v18
	v_mov_b64_e32 v[94:95], v[14:15]
	v_lshl_add_u32 v17, v220, 4, 0
	v_mov_b32_e32 v214, 0
	v_and_b32_e32 v223, 63, v221
	v_mov_b64_e32 v[92:93], v[12:13]
	v_mov_b64_e32 v[90:91], v[10:11]
	v_mov_b64_e32 v[88:89], v[8:9]
	v_mov_b64_e32 v[86:87], v[6:7]
	v_mov_b64_e32 v[84:85], v[4:5]
	v_mov_b64_e32 v[82:83], v[2:3]
	v_mov_b64_e32 v[80:81], v[0:1]
	v_lshl_add_u64 v[210:211], s[2:3], 0, v[200:201]
	v_mad_u32_u24 v200, v16, s23, v17
	v_mad_u32_u24 v225, v222, s23, v17
	s_mov_b32 s20, 0
	s_mov_b32 s56, 64
	v_mov_b32_e32 v215, v214
	v_mov_b32_e32 v212, v214
	v_mov_b32_e32 v213, v214
	v_mov_b32_e32 v48, v214
	v_mov_b32_e32 v49, v214
	v_mov_b32_e32 v50, v214
	v_mov_b32_e32 v51, v214
	v_mov_b32_e32 v52, v214
	v_mov_b32_e32 v53, v214
	v_mov_b32_e32 v54, v214
	v_mov_b32_e32 v55, v214
	v_mov_b32_e32 v56, v214
	v_mov_b32_e32 v57, v214
	v_mov_b32_e32 v58, v214
	v_mov_b32_e32 v59, v214
	v_mov_b32_e32 v60, v214
	v_mov_b32_e32 v61, v214
	v_mov_b32_e32 v62, v214
	v_mov_b32_e32 v63, v214
	v_mov_b32_e32 v64, v214
	v_mov_b32_e32 v65, v214
	v_mov_b32_e32 v66, v214
	v_mov_b32_e32 v67, v214
	v_mov_b32_e32 v68, v214
	v_mov_b32_e32 v69, v214
	v_mov_b32_e32 v70, v214
	v_mov_b32_e32 v71, v214
	v_mov_b32_e32 v72, v214
	v_mov_b32_e32 v73, v214
	v_mov_b32_e32 v74, v214
	v_mov_b32_e32 v75, v214
	v_mov_b32_e32 v76, v214
	v_mov_b32_e32 v77, v214
	v_mov_b32_e32 v78, v214
	v_mov_b32_e32 v79, v214
	v_mov_b32_e32 v16, v214
	v_mov_b32_e32 v17, v214
	v_mov_b32_e32 v18, v214
	v_mov_b32_e32 v19, v214
	v_mov_b32_e32 v20, v214
	v_mov_b32_e32 v21, v214
	v_mov_b32_e32 v22, v214
	v_mov_b32_e32 v23, v214
	v_mov_b32_e32 v24, v214
	v_mov_b32_e32 v25, v214
	v_mov_b32_e32 v26, v214
	v_mov_b32_e32 v27, v214
	v_mov_b32_e32 v28, v214
	v_mov_b32_e32 v29, v214
	v_mov_b32_e32 v30, v214
	v_mov_b32_e32 v31, v214
	v_mov_b32_e32 v32, v214
	v_mov_b32_e32 v33, v214
	v_mov_b32_e32 v34, v214
	v_mov_b32_e32 v35, v214
	v_mov_b32_e32 v36, v214
	v_mov_b32_e32 v37, v214
	v_mov_b32_e32 v38, v214
	v_mov_b32_e32 v39, v214
	v_mov_b32_e32 v40, v214
	v_mov_b32_e32 v41, v214
	v_mov_b32_e32 v42, v214
	v_mov_b32_e32 v43, v214
	v_mov_b32_e32 v44, v214
	v_mov_b32_e32 v45, v214
	v_mov_b32_e32 v46, v214
	v_mov_b32_e32 v47, v214
	s_branch .LBB0_494
	s_nop 0
	s_nop 0
	s_nop 0
	s_nop 0
	s_nop 0
	s_nop 0
	s_nop 0
	s_nop 0
	s_nop 0
	s_nop 0
	s_nop 0
	s_nop 0
	s_nop 0
	s_nop 0

.Lp6e_d0:
	s_waitcnt lgkmcnt(0)
	s_waitcnt vmcnt(0)
	v_cndmask_b32_e64 v104, v100, v120, s[16:17]
	v_cndmask_b32_e64 v105, v101, v121, s[16:17]
	v_cndmask_b32_e64 v106, v102, v122, s[16:17]
	v_cndmask_b32_e64 v107, v103, v123, s[16:17]
	v_cndmask_b32_e64 v108, v100, v156, s[4:5]
	v_cndmask_b32_e64 v109, v101, v157, s[4:5]
	v_cndmask_b32_e64 v110, v102, v158, s[4:5]
	v_cndmask_b32_e64 v111, v103, v159, s[4:5]
	v_mul_f32_dpp v144, v104, v160 row_ror:1 row_mask:0xf bank_mask:0xf
	v_mul_f32_dpp v145, v105, v161 row_ror:1 row_mask:0xf bank_mask:0xf
	v_mul_f32_dpp v146, v106, v162 row_ror:1 row_mask:0xf bank_mask:0xf
	v_mul_f32_dpp v147, v107, v163 row_ror:1 row_mask:0xf bank_mask:0xf
	v_fmac_f32_e32 v144, v100, v164
	v_fmac_f32_e32 v145, v101, v165
	v_fmac_f32_e32 v146, v102, v166
	v_fmac_f32_e32 v147, v103, v167
	v_fmac_f32_dpp v144, v108, v168 row_ror:15 row_mask:0xf bank_mask:0xf
	v_fmac_f32_dpp v145, v109, v169 row_ror:15 row_mask:0xf bank_mask:0xf
	v_fmac_f32_dpp v146, v110, v170 row_ror:15 row_mask:0xf bank_mask:0xf
	v_fmac_f32_dpp v147, v111, v171 row_ror:15 row_mask:0xf bank_mask:0xf
	v_add_f32_e32 v144, v172, v144
	v_add_f32_e32 v145, v173, v145
	v_add_f32_e32 v146, v174, v146
	v_add_f32_e32 v147, v175, v147
	v_cndmask_b32_e64 v104, v96, v124, s[16:17]
	v_cndmask_b32_e64 v105, v97, v125, s[16:17]
	v_cndmask_b32_e64 v106, v98, v126, s[16:17]
	v_cndmask_b32_e64 v107, v99, v127, s[16:17]
	v_cndmask_b32_e64 v108, v96, v152, s[4:5]
	v_cndmask_b32_e64 v109, v97, v153, s[4:5]
	v_cndmask_b32_e64 v110, v98, v154, s[4:5]
	v_cndmask_b32_e64 v111, v99, v155, s[4:5]
	v_mul_f32_dpp v148, v104, v182 row_ror:1 row_mask:0xf bank_mask:0xf
	v_mul_f32_dpp v149, v105, v183 row_ror:1 row_mask:0xf bank_mask:0xf
	v_mul_f32_dpp v150, v106, v184 row_ror:1 row_mask:0xf bank_mask:0xf
	v_mul_f32_dpp v151, v107, v185 row_ror:1 row_mask:0xf bank_mask:0xf
	v_fmac_f32_e32 v148, v96, v186
	v_fmac_f32_e32 v149, v97, v187
	v_fmac_f32_e32 v150, v98, v188
	v_fmac_f32_e32 v151, v99, v189
	v_fmac_f32_dpp v148, v108, v190 row_ror:15 row_mask:0xf bank_mask:0xf
	v_fmac_f32_dpp v149, v109, v191 row_ror:15 row_mask:0xf bank_mask:0xf
	v_fmac_f32_dpp v150, v110, v192 row_ror:15 row_mask:0xf bank_mask:0xf
	v_fmac_f32_dpp v151, v111, v193 row_ror:15 row_mask:0xf bank_mask:0xf
	v_add_f32_e32 v148, v194, v148
	v_add_f32_e32 v149, v195, v149
	v_add_f32_e32 v150, v196, v150
	v_add_f32_e32 v151, v197, v151
	v_fma_f32 v210, |v148|, s10, 1.0
	v_fma_f32 v211, |v149|, s10, 1.0
	v_fma_f32 v212, |v150|, s10, 1.0
	v_fma_f32 v213, |v151|, s10, 1.0
	v_rcp_f32_e32 v210, v210
	v_rcp_f32_e32 v211, v211
	v_rcp_f32_e32 v212, v212
	v_rcp_f32_e32 v213, v213
	v_mul_f32_e32 v218, v148, v148
	v_mul_f32_e32 v219, v149, v149
	v_mul_f32_e32 v220, v150, v150
	v_mul_f32_e32 v221, v151, v151
	v_fmaak_f32 v214, v210, v134, 0xbf3a00e3
	v_fmaak_f32 v215, v211, v134, 0xbf3a00e3
	v_fmaak_f32 v216, v212, v134, 0xbf3a00e3
	v_fmaak_f32 v217, v213, v134, 0xbf3a00e3
	v_fmaak_f32 v214, v214, v210, 0x3f35f0e3
	v_fmaak_f32 v215, v215, v211, 0x3f35f0e3
	v_fmaak_f32 v216, v216, v212, 0x3f35f0e3
	v_fmaak_f32 v217, v217, v213, 0x3f35f0e3
	v_fmaak_f32 v214, v214, v210, 0xbe11a98e
	v_fmaak_f32 v215, v215, v211, 0xbe11a98e
	v_fmaak_f32 v216, v216, v212, 0xbe11a98e
	v_fmaak_f32 v217, v217, v213, 0xbe11a98e
	v_fmaak_f32 v214, v214, v210, 0x3e027906
	v_fmaak_f32 v215, v215, v211, 0x3e027906
	v_fmaak_f32 v216, v216, v212, 0x3e027906
	v_fmaak_f32 v217, v217, v213, 0x3e027906
	v_mul_f32_e32 v214, v214, v210
	v_mul_f32_e32 v215, v215, v211
	v_mul_f32_e32 v216, v216, v212
	v_mul_f32_e32 v217, v217, v213
	v_mul_f32_e32 v218, 0xbf38aa3b, v218
	v_mul_f32_e32 v219, 0xbf38aa3b, v219
	v_mul_f32_e32 v220, 0xbf38aa3b, v220
	v_mul_f32_e32 v221, 0xbf38aa3b, v221
	v_exp_f32_e32 v218, v218
	v_exp_f32_e32 v219, v219
	v_exp_f32_e32 v220, v220
	v_exp_f32_e32 v221, v221
	v_mul_f32_e32 v218, v218, v214
	v_mul_f32_e32 v219, v219, v215
	v_mul_f32_e32 v220, v220, v216
	v_mul_f32_e32 v221, v221, v217
	v_max_f32_e32 v210, 0, v148
	v_max_f32_e32 v211, 0, v149
	v_max_f32_e32 v212, 0, v150
	v_max_f32_e32 v213, 0, v151
	v_fma_f32 v222, -|v148|, v218, v210
	v_fma_f32 v223, -|v149|, v219, v211
	v_fma_f32 v224, -|v150|, v220, v212
	v_fma_f32 v225, -|v151|, v221, v213
	v_mul_f32_e32 v144, v144, v222
	v_mul_f32_e32 v145, v145, v223
	v_mul_f32_e32 v146, v146, v224
	v_mul_f32_e32 v147, v147, v225
	v_cvt_pk_bf16_f32 v202, v144, v145
	v_cvt_pk_bf16_f32 v203, v146, v147
	ds_read_b128 v[120:123], v135 offset:512
	ds_read_b128 v[124:127], v135 offset:640
	v_cndmask_b32_e64 v104, v156, v100, s[16:17]
	v_cndmask_b32_e64 v105, v157, v101, s[16:17]
	v_cndmask_b32_e64 v106, v158, v102, s[16:17]
	v_cndmask_b32_e64 v107, v159, v103, s[16:17]
	v_cndmask_b32_e64 v108, v156, v140, s[4:5]
	v_cndmask_b32_e64 v109, v157, v141, s[4:5]
	v_cndmask_b32_e64 v110, v158, v142, s[4:5]
	v_cndmask_b32_e64 v111, v159, v143, s[4:5]
	v_mul_f32_dpp v144, v104, v160 row_ror:1 row_mask:0xf bank_mask:0xf
	v_mul_f32_dpp v145, v105, v161 row_ror:1 row_mask:0xf bank_mask:0xf
	v_mul_f32_dpp v146, v106, v162 row_ror:1 row_mask:0xf bank_mask:0xf
	v_mul_f32_dpp v147, v107, v163 row_ror:1 row_mask:0xf bank_mask:0xf
	v_fmac_f32_e32 v144, v156, v164
	v_fmac_f32_e32 v145, v157, v165
	v_fmac_f32_e32 v146, v158, v166
	v_fmac_f32_e32 v147, v159, v167
	v_fmac_f32_dpp v144, v108, v168 row_ror:15 row_mask:0xf bank_mask:0xf
	v_fmac_f32_dpp v145, v109, v169 row_ror:15 row_mask:0xf bank_mask:0xf
	v_fmac_f32_dpp v146, v110, v170 row_ror:15 row_mask:0xf bank_mask:0xf
	v_fmac_f32_dpp v147, v111, v171 row_ror:15 row_mask:0xf bank_mask:0xf
	v_add_f32_e32 v144, v172, v144
	v_add_f32_e32 v145, v173, v145
	v_add_f32_e32 v146, v174, v146
	v_add_f32_e32 v147, v175, v147
	v_cndmask_b32_e64 v104, v152, v96, s[16:17]
	v_cndmask_b32_e64 v105, v153, v97, s[16:17]
	v_cndmask_b32_e64 v106, v154, v98, s[16:17]
	v_cndmask_b32_e64 v107, v155, v99, s[16:17]
	v_cndmask_b32_e64 v108, v152, v136, s[4:5]
	v_cndmask_b32_e64 v109, v153, v137, s[4:5]
	v_cndmask_b32_e64 v110, v154, v138, s[4:5]
	v_cndmask_b32_e64 v111, v155, v139, s[4:5]
	v_mul_f32_dpp v148, v104, v182 row_ror:1 row_mask:0xf bank_mask:0xf
	v_mul_f32_dpp v149, v105, v183 row_ror:1 row_mask:0xf bank_mask:0xf
	v_mul_f32_dpp v150, v106, v184 row_ror:1 row_mask:0xf bank_mask:0xf
	v_mul_f32_dpp v151, v107, v185 row_ror:1 row_mask:0xf bank_mask:0xf
	v_fmac_f32_e32 v148, v152, v186
	v_fmac_f32_e32 v149, v153, v187
	v_fmac_f32_e32 v150, v154, v188
	v_fmac_f32_e32 v151, v155, v189
	v_fmac_f32_dpp v148, v108, v190 row_ror:15 row_mask:0xf bank_mask:0xf
	v_fmac_f32_dpp v149, v109, v191 row_ror:15 row_mask:0xf bank_mask:0xf
	v_fmac_f32_dpp v150, v110, v192 row_ror:15 row_mask:0xf bank_mask:0xf
	v_fmac_f32_dpp v151, v111, v193 row_ror:15 row_mask:0xf bank_mask:0xf
	v_add_f32_e32 v148, v194, v148
	v_add_f32_e32 v149, v195, v149
	v_add_f32_e32 v150, v196, v150
	v_add_f32_e32 v151, v197, v151
	v_fma_f32 v210, |v148|, s10, 1.0
	v_fma_f32 v211, |v149|, s10, 1.0
	v_fma_f32 v212, |v150|, s10, 1.0
	v_fma_f32 v213, |v151|, s10, 1.0
	v_rcp_f32_e32 v210, v210
	v_rcp_f32_e32 v211, v211
	v_rcp_f32_e32 v212, v212
	v_rcp_f32_e32 v213, v213
	v_mul_f32_e32 v218, v148, v148
	v_mul_f32_e32 v219, v149, v149
	v_mul_f32_e32 v220, v150, v150
	v_mul_f32_e32 v221, v151, v151
	v_fmaak_f32 v214, v210, v134, 0xbf3a00e3
	v_fmaak_f32 v215, v211, v134, 0xbf3a00e3
	v_fmaak_f32 v216, v212, v134, 0xbf3a00e3
	v_fmaak_f32 v217, v213, v134, 0xbf3a00e3
	v_fmaak_f32 v214, v214, v210, 0x3f35f0e3
	v_fmaak_f32 v215, v215, v211, 0x3f35f0e3
	v_fmaak_f32 v216, v216, v212, 0x3f35f0e3
	v_fmaak_f32 v217, v217, v213, 0x3f35f0e3
	v_fmaak_f32 v214, v214, v210, 0xbe11a98e
	v_fmaak_f32 v215, v215, v211, 0xbe11a98e
	v_fmaak_f32 v216, v216, v212, 0xbe11a98e
	v_fmaak_f32 v217, v217, v213, 0xbe11a98e
	v_fmaak_f32 v214, v214, v210, 0x3e027906
	v_fmaak_f32 v215, v215, v211, 0x3e027906
	v_fmaak_f32 v216, v216, v212, 0x3e027906
	v_fmaak_f32 v217, v217, v213, 0x3e027906
	v_mul_f32_e32 v214, v214, v210
	v_mul_f32_e32 v215, v215, v211
	v_mul_f32_e32 v216, v216, v212
	v_mul_f32_e32 v217, v217, v213
	v_mul_f32_e32 v218, 0xbf38aa3b, v218
	v_mul_f32_e32 v219, 0xbf38aa3b, v219
	v_mul_f32_e32 v220, 0xbf38aa3b, v220
	v_mul_f32_e32 v221, 0xbf38aa3b, v221
	v_exp_f32_e32 v218, v218
	v_exp_f32_e32 v219, v219
	v_exp_f32_e32 v220, v220
	v_exp_f32_e32 v221, v221
	v_mul_f32_e32 v218, v218, v214
	v_mul_f32_e32 v219, v219, v215
	v_mul_f32_e32 v220, v220, v216
	v_mul_f32_e32 v221, v221, v217
	v_max_f32_e32 v210, 0, v148
	v_max_f32_e32 v211, 0, v149
	v_max_f32_e32 v212, 0, v150
	v_max_f32_e32 v213, 0, v151
	v_fma_f32 v222, -|v148|, v218, v210
	v_fma_f32 v223, -|v149|, v219, v211
	v_fma_f32 v224, -|v150|, v220, v212
	v_fma_f32 v225, -|v151|, v221, v213
	v_mul_f32_e32 v144, v144, v222
	v_mul_f32_e32 v145, v145, v223
	v_mul_f32_e32 v146, v146, v224
	v_mul_f32_e32 v147, v147, v225
	v_cvt_pk_bf16_f32 v128, v144, v145
	v_cvt_pk_bf16_f32 v129, v146, v147
	v_cndmask_b32_e64 v104, v140, v156, s[16:17]
	v_cndmask_b32_e64 v105, v141, v157, s[16:17]
	v_cndmask_b32_e64 v106, v142, v158, s[16:17]
	v_cndmask_b32_e64 v107, v143, v159, s[16:17]
	v_cndmask_b32_e64 v108, v140, v88, s[4:5]
	v_cndmask_b32_e64 v109, v141, v89, s[4:5]
	v_cndmask_b32_e64 v110, v142, v90, s[4:5]
	v_cndmask_b32_e64 v111, v143, v91, s[4:5]
	v_mul_f32_dpp v144, v104, v160 row_ror:1 row_mask:0xf bank_mask:0xf
	v_mul_f32_dpp v145, v105, v161 row_ror:1 row_mask:0xf bank_mask:0xf
	v_mul_f32_dpp v146, v106, v162 row_ror:1 row_mask:0xf bank_mask:0xf
	v_mul_f32_dpp v147, v107, v163 row_ror:1 row_mask:0xf bank_mask:0xf
	v_fmac_f32_e32 v144, v140, v164
	v_fmac_f32_e32 v145, v141, v165
	v_fmac_f32_e32 v146, v142, v166
	v_fmac_f32_e32 v147, v143, v167
	v_fmac_f32_dpp v144, v108, v168 row_ror:15 row_mask:0xf bank_mask:0xf
	v_fmac_f32_dpp v145, v109, v169 row_ror:15 row_mask:0xf bank_mask:0xf
	v_fmac_f32_dpp v146, v110, v170 row_ror:15 row_mask:0xf bank_mask:0xf
	v_fmac_f32_dpp v147, v111, v171 row_ror:15 row_mask:0xf bank_mask:0xf
	v_add_f32_e32 v144, v172, v144
	v_add_f32_e32 v145, v173, v145
	v_add_f32_e32 v146, v174, v146
	v_add_f32_e32 v147, v175, v147
	v_cndmask_b32_e64 v104, v136, v152, s[16:17]
	v_cndmask_b32_e64 v105, v137, v153, s[16:17]
	v_cndmask_b32_e64 v106, v138, v154, s[16:17]
	v_cndmask_b32_e64 v107, v139, v155, s[16:17]
	v_cndmask_b32_e64 v108, v136, v80, s[4:5]
	v_cndmask_b32_e64 v109, v137, v81, s[4:5]
	v_cndmask_b32_e64 v110, v138, v82, s[4:5]
	v_cndmask_b32_e64 v111, v139, v83, s[4:5]
	v_mul_f32_dpp v148, v104, v182 row_ror:1 row_mask:0xf bank_mask:0xf
	v_mul_f32_dpp v149, v105, v183 row_ror:1 row_mask:0xf bank_mask:0xf
	v_mul_f32_dpp v150, v106, v184 row_ror:1 row_mask:0xf bank_mask:0xf
	v_mul_f32_dpp v151, v107, v185 row_ror:1 row_mask:0xf bank_mask:0xf
	v_fmac_f32_e32 v148, v136, v186
	v_fmac_f32_e32 v149, v137, v187
	v_fmac_f32_e32 v150, v138, v188
	v_fmac_f32_e32 v151, v139, v189
	v_fmac_f32_dpp v148, v108, v190 row_ror:15 row_mask:0xf bank_mask:0xf
	v_fmac_f32_dpp v149, v109, v191 row_ror:15 row_mask:0xf bank_mask:0xf
	v_fmac_f32_dpp v150, v110, v192 row_ror:15 row_mask:0xf bank_mask:0xf
	v_fmac_f32_dpp v151, v111, v193 row_ror:15 row_mask:0xf bank_mask:0xf
	v_add_f32_e32 v148, v194, v148
	v_add_f32_e32 v149, v195, v149
	v_add_f32_e32 v150, v196, v150
	v_add_f32_e32 v151, v197, v151
	v_fma_f32 v210, |v148|, s10, 1.0
	v_fma_f32 v211, |v149|, s10, 1.0
	v_fma_f32 v212, |v150|, s10, 1.0
	v_fma_f32 v213, |v151|, s10, 1.0
	v_rcp_f32_e32 v210, v210
	v_rcp_f32_e32 v211, v211
	v_rcp_f32_e32 v212, v212
	v_rcp_f32_e32 v213, v213
	v_mul_f32_e32 v218, v148, v148
	v_mul_f32_e32 v219, v149, v149
	v_mul_f32_e32 v220, v150, v150
	v_mul_f32_e32 v221, v151, v151
	v_fmaak_f32 v214, v210, v134, 0xbf3a00e3
	v_fmaak_f32 v215, v211, v134, 0xbf3a00e3
	v_fmaak_f32 v216, v212, v134, 0xbf3a00e3
	v_fmaak_f32 v217, v213, v134, 0xbf3a00e3
	v_fmaak_f32 v214, v214, v210, 0x3f35f0e3
	v_fmaak_f32 v215, v215, v211, 0x3f35f0e3
	v_fmaak_f32 v216, v216, v212, 0x3f35f0e3
	v_fmaak_f32 v217, v217, v213, 0x3f35f0e3
	v_fmaak_f32 v214, v214, v210, 0xbe11a98e
	v_fmaak_f32 v215, v215, v211, 0xbe11a98e
	v_fmaak_f32 v216, v216, v212, 0xbe11a98e
	v_fmaak_f32 v217, v217, v213, 0xbe11a98e
	v_fmaak_f32 v214, v214, v210, 0x3e027906
	v_fmaak_f32 v215, v215, v211, 0x3e027906
	v_fmaak_f32 v216, v216, v212, 0x3e027906
	v_fmaak_f32 v217, v217, v213, 0x3e027906
	v_mul_f32_e32 v214, v214, v210
	v_mul_f32_e32 v215, v215, v211
	v_mul_f32_e32 v216, v216, v212
	v_mul_f32_e32 v217, v217, v213
	v_mul_f32_e32 v218, 0xbf38aa3b, v218
	v_mul_f32_e32 v219, 0xbf38aa3b, v219
	v_mul_f32_e32 v220, 0xbf38aa3b, v220
	v_mul_f32_e32 v221, 0xbf38aa3b, v221
	v_exp_f32_e32 v218, v218
	v_exp_f32_e32 v219, v219
	v_exp_f32_e32 v220, v220
	v_exp_f32_e32 v221, v221
	v_mul_f32_e32 v218, v218, v214
	v_mul_f32_e32 v219, v219, v215
	v_mul_f32_e32 v220, v220, v216
	v_mul_f32_e32 v221, v221, v217
	v_max_f32_e32 v210, 0, v148
	v_max_f32_e32 v211, 0, v149
	v_max_f32_e32 v212, 0, v150
	v_max_f32_e32 v213, 0, v151
	v_fma_f32 v222, -|v148|, v218, v210
	v_fma_f32 v223, -|v149|, v219, v211
	v_fma_f32 v224, -|v150|, v220, v212
	v_fma_f32 v225, -|v151|, v221, v213
	v_mul_f32_e32 v144, v144, v222
	v_mul_f32_e32 v145, v145, v223
	v_mul_f32_e32 v146, v146, v224
	v_mul_f32_e32 v147, v147, v225
	v_cvt_pk_bf16_f32 v100, v144, v145
	v_cvt_pk_bf16_f32 v101, v146, v147
	s_waitcnt lgkmcnt(0)
	v_cndmask_b32_e64 v104, v88, v140, s[16:17]
	v_cndmask_b32_e64 v105, v89, v141, s[16:17]
	v_cndmask_b32_e64 v106, v90, v142, s[16:17]
	v_cndmask_b32_e64 v107, v91, v143, s[16:17]
	v_cndmask_b32_e64 v108, v88, v120, s[4:5]
	v_cndmask_b32_e64 v109, v89, v121, s[4:5]
	v_cndmask_b32_e64 v110, v90, v122, s[4:5]
	v_cndmask_b32_e64 v111, v91, v123, s[4:5]
	v_mul_f32_dpp v144, v104, v160 row_ror:1 row_mask:0xf bank_mask:0xf
	v_mul_f32_dpp v145, v105, v161 row_ror:1 row_mask:0xf bank_mask:0xf
	v_mul_f32_dpp v146, v106, v162 row_ror:1 row_mask:0xf bank_mask:0xf
	v_mul_f32_dpp v147, v107, v163 row_ror:1 row_mask:0xf bank_mask:0xf
	v_fmac_f32_e32 v144, v88, v164
	v_fmac_f32_e32 v145, v89, v165
	v_fmac_f32_e32 v146, v90, v166
	v_fmac_f32_e32 v147, v91, v167
	v_fmac_f32_dpp v144, v108, v168 row_ror:15 row_mask:0xf bank_mask:0xf
	v_fmac_f32_dpp v145, v109, v169 row_ror:15 row_mask:0xf bank_mask:0xf
	v_fmac_f32_dpp v146, v110, v170 row_ror:15 row_mask:0xf bank_mask:0xf
	v_fmac_f32_dpp v147, v111, v171 row_ror:15 row_mask:0xf bank_mask:0xf
	v_add_f32_e32 v144, v172, v144
	v_add_f32_e32 v145, v173, v145
	v_add_f32_e32 v146, v174, v146
	v_add_f32_e32 v147, v175, v147
	v_cndmask_b32_e64 v104, v80, v136, s[16:17]
	v_cndmask_b32_e64 v105, v81, v137, s[16:17]
	v_cndmask_b32_e64 v106, v82, v138, s[16:17]
	v_cndmask_b32_e64 v107, v83, v139, s[16:17]
	v_cndmask_b32_e64 v108, v80, v124, s[4:5]
	v_cndmask_b32_e64 v109, v81, v125, s[4:5]
	v_cndmask_b32_e64 v110, v82, v126, s[4:5]
	v_cndmask_b32_e64 v111, v83, v127, s[4:5]
	v_mul_f32_dpp v148, v104, v182 row_ror:1 row_mask:0xf bank_mask:0xf
	v_mul_f32_dpp v149, v105, v183 row_ror:1 row_mask:0xf bank_mask:0xf
	v_mul_f32_dpp v150, v106, v184 row_ror:1 row_mask:0xf bank_mask:0xf
	v_mul_f32_dpp v151, v107, v185 row_ror:1 row_mask:0xf bank_mask:0xf
	v_fmac_f32_e32 v148, v80, v186
	v_fmac_f32_e32 v149, v81, v187
	v_fmac_f32_e32 v150, v82, v188
	v_fmac_f32_e32 v151, v83, v189
	v_fmac_f32_dpp v148, v108, v190 row_ror:15 row_mask:0xf bank_mask:0xf
	v_fmac_f32_dpp v149, v109, v191 row_ror:15 row_mask:0xf bank_mask:0xf
	v_fmac_f32_dpp v150, v110, v192 row_ror:15 row_mask:0xf bank_mask:0xf
	v_fmac_f32_dpp v151, v111, v193 row_ror:15 row_mask:0xf bank_mask:0xf
	v_add_f32_e32 v148, v194, v148
	v_add_f32_e32 v149, v195, v149
	v_add_f32_e32 v150, v196, v150
	v_add_f32_e32 v151, v197, v151
	v_fma_f32 v210, |v148|, s10, 1.0
	v_fma_f32 v211, |v149|, s10, 1.0
	v_fma_f32 v212, |v150|, s10, 1.0
	v_fma_f32 v213, |v151|, s10, 1.0
	v_rcp_f32_e32 v210, v210
	v_rcp_f32_e32 v211, v211
	v_rcp_f32_e32 v212, v212
	v_rcp_f32_e32 v213, v213
	v_mul_f32_e32 v218, v148, v148
	v_mul_f32_e32 v219, v149, v149
	v_mul_f32_e32 v220, v150, v150
	v_mul_f32_e32 v221, v151, v151
	v_fmaak_f32 v214, v210, v134, 0xbf3a00e3
	v_fmaak_f32 v215, v211, v134, 0xbf3a00e3
	v_fmaak_f32 v216, v212, v134, 0xbf3a00e3
	v_fmaak_f32 v217, v213, v134, 0xbf3a00e3
	v_fmaak_f32 v214, v214, v210, 0x3f35f0e3
	v_fmaak_f32 v215, v215, v211, 0x3f35f0e3
	v_fmaak_f32 v216, v216, v212, 0x3f35f0e3
	v_fmaak_f32 v217, v217, v213, 0x3f35f0e3
	v_fmaak_f32 v214, v214, v210, 0xbe11a98e
	v_fmaak_f32 v215, v215, v211, 0xbe11a98e
	v_fmaak_f32 v216, v216, v212, 0xbe11a98e
	v_fmaak_f32 v217, v217, v213, 0xbe11a98e
	v_fmaak_f32 v214, v214, v210, 0x3e027906
	v_fmaak_f32 v215, v215, v211, 0x3e027906
	v_fmaak_f32 v216, v216, v212, 0x3e027906
	v_fmaak_f32 v217, v217, v213, 0x3e027906
	v_mul_f32_e32 v214, v214, v210
	v_mul_f32_e32 v215, v215, v211
	v_mul_f32_e32 v216, v216, v212
	v_mul_f32_e32 v217, v217, v213
	v_mul_f32_e32 v218, 0xbf38aa3b, v218
	v_mul_f32_e32 v219, 0xbf38aa3b, v219
	v_mul_f32_e32 v220, 0xbf38aa3b, v220
	v_mul_f32_e32 v221, 0xbf38aa3b, v221
	v_exp_f32_e32 v218, v218
	v_exp_f32_e32 v219, v219
	v_exp_f32_e32 v220, v220
	v_exp_f32_e32 v221, v221
	v_mul_f32_e32 v218, v218, v214
	v_mul_f32_e32 v219, v219, v215
	v_mul_f32_e32 v220, v220, v216
	v_mul_f32_e32 v221, v221, v217
	v_max_f32_e32 v210, 0, v148
	v_max_f32_e32 v211, 0, v149
	v_max_f32_e32 v212, 0, v150
	v_max_f32_e32 v213, 0, v151
	v_fma_f32 v222, -|v148|, v218, v210
	v_fma_f32 v223, -|v149|, v219, v211
	v_fma_f32 v224, -|v150|, v220, v212
	v_fma_f32 v225, -|v151|, v221, v213
	v_mul_f32_e32 v144, v144, v222
	v_mul_f32_e32 v145, v145, v223
	v_mul_f32_e32 v146, v146, v224
	v_mul_f32_e32 v147, v147, v225
	v_cvt_pk_bf16_f32 v96, v144, v145
	v_cvt_pk_bf16_f32 v97, v146, v147
	ds_read_b128 v[120:123], v228 offset:1024
	ds_read_b128 v[124:127], v228 offset:1152
	s_waitcnt lgkmcnt(0)
	v_cndmask_b32_e64 v104, v92, v120, s[16:17]
	v_cndmask_b32_e64 v105, v93, v121, s[16:17]
	v_cndmask_b32_e64 v106, v94, v122, s[16:17]
	v_cndmask_b32_e64 v107, v95, v123, s[16:17]
	v_cndmask_b32_e64 v108, v92, v116, s[4:5]
	v_cndmask_b32_e64 v109, v93, v117, s[4:5]
	v_cndmask_b32_e64 v110, v94, v118, s[4:5]
	v_cndmask_b32_e64 v111, v95, v119, s[4:5]
	v_mul_f32_dpp v144, v104, v160 row_ror:1 row_mask:0xf bank_mask:0xf
	v_mul_f32_dpp v145, v105, v161 row_ror:1 row_mask:0xf bank_mask:0xf
	v_mul_f32_dpp v146, v106, v162 row_ror:1 row_mask:0xf bank_mask:0xf
	v_mul_f32_dpp v147, v107, v163 row_ror:1 row_mask:0xf bank_mask:0xf
	v_fmac_f32_e32 v144, v92, v164
	v_fmac_f32_e32 v145, v93, v165
	v_fmac_f32_e32 v146, v94, v166
	v_fmac_f32_e32 v147, v95, v167
	v_fmac_f32_dpp v144, v108, v168 row_ror:15 row_mask:0xf bank_mask:0xf
	v_fmac_f32_dpp v145, v109, v169 row_ror:15 row_mask:0xf bank_mask:0xf
	v_fmac_f32_dpp v146, v110, v170 row_ror:15 row_mask:0xf bank_mask:0xf
	v_fmac_f32_dpp v147, v111, v171 row_ror:15 row_mask:0xf bank_mask:0xf
	v_add_f32_e32 v144, v172, v144
	v_add_f32_e32 v145, v173, v145
	v_add_f32_e32 v146, v174, v146
	v_add_f32_e32 v147, v175, v147
	v_cndmask_b32_e64 v104, v36, v124, s[16:17]
	v_cndmask_b32_e64 v105, v37, v125, s[16:17]
	v_cndmask_b32_e64 v106, v38, v126, s[16:17]
	v_cndmask_b32_e64 v107, v39, v127, s[16:17]
	v_cndmask_b32_e64 v108, v36, v112, s[4:5]
	v_cndmask_b32_e64 v109, v37, v113, s[4:5]
	v_cndmask_b32_e64 v110, v38, v114, s[4:5]
	v_cndmask_b32_e64 v111, v39, v115, s[4:5]
	v_mul_f32_dpp v148, v104, v182 row_ror:1 row_mask:0xf bank_mask:0xf
	v_mul_f32_dpp v149, v105, v183 row_ror:1 row_mask:0xf bank_mask:0xf
	v_mul_f32_dpp v150, v106, v184 row_ror:1 row_mask:0xf bank_mask:0xf
	v_mul_f32_dpp v151, v107, v185 row_ror:1 row_mask:0xf bank_mask:0xf
	v_fmac_f32_e32 v148, v36, v186
	v_fmac_f32_e32 v149, v37, v187
	v_fmac_f32_e32 v150, v38, v188
	v_fmac_f32_e32 v151, v39, v189
	v_fmac_f32_dpp v148, v108, v190 row_ror:15 row_mask:0xf bank_mask:0xf
	v_fmac_f32_dpp v149, v109, v191 row_ror:15 row_mask:0xf bank_mask:0xf
	v_fmac_f32_dpp v150, v110, v192 row_ror:15 row_mask:0xf bank_mask:0xf
	v_fmac_f32_dpp v151, v111, v193 row_ror:15 row_mask:0xf bank_mask:0xf
	v_add_f32_e32 v148, v194, v148
	v_add_f32_e32 v149, v195, v149
	v_add_f32_e32 v150, v196, v150
	v_add_f32_e32 v151, v197, v151
	v_fma_f32 v210, |v148|, s10, 1.0
	v_fma_f32 v211, |v149|, s10, 1.0
	v_fma_f32 v212, |v150|, s10, 1.0
	v_fma_f32 v213, |v151|, s10, 1.0
	v_rcp_f32_e32 v210, v210
	v_rcp_f32_e32 v211, v211
	v_rcp_f32_e32 v212, v212
	v_rcp_f32_e32 v213, v213
	v_mul_f32_e32 v218, v148, v148
	v_mul_f32_e32 v219, v149, v149
	v_mul_f32_e32 v220, v150, v150
	v_mul_f32_e32 v221, v151, v151
	v_fmaak_f32 v214, v210, v134, 0xbf3a00e3
	v_fmaak_f32 v215, v211, v134, 0xbf3a00e3
	v_fmaak_f32 v216, v212, v134, 0xbf3a00e3
	v_fmaak_f32 v217, v213, v134, 0xbf3a00e3
	v_fmaak_f32 v214, v214, v210, 0x3f35f0e3
	v_fmaak_f32 v215, v215, v211, 0x3f35f0e3
	v_fmaak_f32 v216, v216, v212, 0x3f35f0e3
	v_fmaak_f32 v217, v217, v213, 0x3f35f0e3
	v_fmaak_f32 v214, v214, v210, 0xbe11a98e
	v_fmaak_f32 v215, v215, v211, 0xbe11a98e
	v_fmaak_f32 v216, v216, v212, 0xbe11a98e
	v_fmaak_f32 v217, v217, v213, 0xbe11a98e
	v_fmaak_f32 v214, v214, v210, 0x3e027906
	v_fmaak_f32 v215, v215, v211, 0x3e027906
	v_fmaak_f32 v216, v216, v212, 0x3e027906
	v_fmaak_f32 v217, v217, v213, 0x3e027906
	v_mul_f32_e32 v214, v214, v210
	v_mul_f32_e32 v215, v215, v211
	v_mul_f32_e32 v216, v216, v212
	v_mul_f32_e32 v217, v217, v213
	v_mul_f32_e32 v218, 0xbf38aa3b, v218
	v_mul_f32_e32 v219, 0xbf38aa3b, v219
	v_mul_f32_e32 v220, 0xbf38aa3b, v220
	v_mul_f32_e32 v221, 0xbf38aa3b, v221
	v_exp_f32_e32 v218, v218
	v_exp_f32_e32 v219, v219
	v_exp_f32_e32 v220, v220
	v_exp_f32_e32 v221, v221
	v_mul_f32_e32 v218, v218, v214
	v_mul_f32_e32 v219, v219, v215
	v_mul_f32_e32 v220, v220, v216
	v_mul_f32_e32 v221, v221, v217
	v_max_f32_e32 v210, 0, v148
	v_max_f32_e32 v211, 0, v149
	v_max_f32_e32 v212, 0, v150
	v_max_f32_e32 v213, 0, v151
	v_fma_f32 v222, -|v148|, v218, v210
	v_fma_f32 v223, -|v149|, v219, v211
	v_fma_f32 v224, -|v150|, v220, v212
	v_fma_f32 v225, -|v151|, v221, v213
	v_mul_f32_e32 v144, v144, v222
	v_mul_f32_e32 v145, v145, v223
	v_mul_f32_e32 v146, v146, v224
	v_mul_f32_e32 v147, v147, v225
	v_cvt_pk_bf16_f32 v156, v144, v145
	v_cvt_pk_bf16_f32 v157, v146, v147
	s_and_b64 vcc, exec, s[66:67]
	s_cbranch_vccz .Lp6e_z3
	ds_read_b128 v[120:123], v135 offset:1536
	ds_read_b128 v[124:127], v135 offset:1664
	s_branch .Lp6e_d3

.Lp6e_d3:
	v_cndmask_b32_e64 v104, v116, v92, s[16:17]
	v_cndmask_b32_e64 v105, v117, v93, s[16:17]
	v_cndmask_b32_e64 v106, v118, v94, s[16:17]
	v_cndmask_b32_e64 v107, v119, v95, s[16:17]
	v_cndmask_b32_e64 v108, v116, v76, s[4:5]
	v_cndmask_b32_e64 v109, v117, v77, s[4:5]
	v_cndmask_b32_e64 v110, v118, v78, s[4:5]
	v_cndmask_b32_e64 v111, v119, v79, s[4:5]
	v_mul_f32_dpp v144, v104, v160 row_ror:1 row_mask:0xf bank_mask:0xf
	v_mul_f32_dpp v145, v105, v161 row_ror:1 row_mask:0xf bank_mask:0xf
	v_mul_f32_dpp v146, v106, v162 row_ror:1 row_mask:0xf bank_mask:0xf
	v_mul_f32_dpp v147, v107, v163 row_ror:1 row_mask:0xf bank_mask:0xf
	v_fmac_f32_e32 v144, v116, v164
	v_fmac_f32_e32 v145, v117, v165
	v_fmac_f32_e32 v146, v118, v166
	v_fmac_f32_e32 v147, v119, v167
	v_fmac_f32_dpp v144, v108, v168 row_ror:15 row_mask:0xf bank_mask:0xf
	v_fmac_f32_dpp v145, v109, v169 row_ror:15 row_mask:0xf bank_mask:0xf
	v_fmac_f32_dpp v146, v110, v170 row_ror:15 row_mask:0xf bank_mask:0xf
	v_fmac_f32_dpp v147, v111, v171 row_ror:15 row_mask:0xf bank_mask:0xf
	v_add_f32_e32 v144, v172, v144
	v_add_f32_e32 v145, v173, v145
	v_add_f32_e32 v146, v174, v146
	v_add_f32_e32 v147, v175, v147
	v_cndmask_b32_e64 v104, v112, v36, s[16:17]
	v_cndmask_b32_e64 v105, v113, v37, s[16:17]
	v_cndmask_b32_e64 v106, v114, v38, s[16:17]
	v_cndmask_b32_e64 v107, v115, v39, s[16:17]
	v_cndmask_b32_e64 v108, v112, v72, s[4:5]
	v_cndmask_b32_e64 v109, v113, v73, s[4:5]
	v_cndmask_b32_e64 v110, v114, v74, s[4:5]
	v_cndmask_b32_e64 v111, v115, v75, s[4:5]
	v_mul_f32_dpp v148, v104, v182 row_ror:1 row_mask:0xf bank_mask:0xf
	v_mul_f32_dpp v149, v105, v183 row_ror:1 row_mask:0xf bank_mask:0xf
	v_mul_f32_dpp v150, v106, v184 row_ror:1 row_mask:0xf bank_mask:0xf
	v_mul_f32_dpp v151, v107, v185 row_ror:1 row_mask:0xf bank_mask:0xf
	v_fmac_f32_e32 v148, v112, v186
	v_fmac_f32_e32 v149, v113, v187
	v_fmac_f32_e32 v150, v114, v188
	v_fmac_f32_e32 v151, v115, v189
	v_fmac_f32_dpp v148, v108, v190 row_ror:15 row_mask:0xf bank_mask:0xf
	v_fmac_f32_dpp v149, v109, v191 row_ror:15 row_mask:0xf bank_mask:0xf
	v_fmac_f32_dpp v150, v110, v192 row_ror:15 row_mask:0xf bank_mask:0xf
	v_fmac_f32_dpp v151, v111, v193 row_ror:15 row_mask:0xf bank_mask:0xf
	v_add_f32_e32 v148, v194, v148
	v_add_f32_e32 v149, v195, v149
	v_add_f32_e32 v150, v196, v150
	v_add_f32_e32 v151, v197, v151
	v_fma_f32 v210, |v148|, s10, 1.0
	v_fma_f32 v211, |v149|, s10, 1.0
	v_fma_f32 v212, |v150|, s10, 1.0
	v_fma_f32 v213, |v151|, s10, 1.0
	v_rcp_f32_e32 v210, v210
	v_rcp_f32_e32 v211, v211
	v_rcp_f32_e32 v212, v212
	v_rcp_f32_e32 v213, v213
	v_mul_f32_e32 v218, v148, v148
	v_mul_f32_e32 v219, v149, v149
	v_mul_f32_e32 v220, v150, v150
	v_mul_f32_e32 v221, v151, v151
	v_fmaak_f32 v214, v210, v134, 0xbf3a00e3
	v_fmaak_f32 v215, v211, v134, 0xbf3a00e3
	v_fmaak_f32 v216, v212, v134, 0xbf3a00e3
	v_fmaak_f32 v217, v213, v134, 0xbf3a00e3
	v_fmaak_f32 v214, v214, v210, 0x3f35f0e3
	v_fmaak_f32 v215, v215, v211, 0x3f35f0e3
	v_fmaak_f32 v216, v216, v212, 0x3f35f0e3
	v_fmaak_f32 v217, v217, v213, 0x3f35f0e3
	v_fmaak_f32 v214, v214, v210, 0xbe11a98e
	v_fmaak_f32 v215, v215, v211, 0xbe11a98e
	v_fmaak_f32 v216, v216, v212, 0xbe11a98e
	v_fmaak_f32 v217, v217, v213, 0xbe11a98e
	v_fmaak_f32 v214, v214, v210, 0x3e027906
	v_fmaak_f32 v215, v215, v211, 0x3e027906
	v_fmaak_f32 v216, v216, v212, 0x3e027906
	v_fmaak_f32 v217, v217, v213, 0x3e027906
	v_mul_f32_e32 v214, v214, v210
	v_mul_f32_e32 v215, v215, v211
	v_mul_f32_e32 v216, v216, v212
	v_mul_f32_e32 v217, v217, v213
	v_mul_f32_e32 v218, 0xbf38aa3b, v218
	v_mul_f32_e32 v219, 0xbf38aa3b, v219
	v_mul_f32_e32 v220, 0xbf38aa3b, v220
	v_mul_f32_e32 v221, 0xbf38aa3b, v221
	v_exp_f32_e32 v218, v218
	v_exp_f32_e32 v219, v219
	v_exp_f32_e32 v220, v220
	v_exp_f32_e32 v221, v221
	v_mul_f32_e32 v218, v218, v214
	v_mul_f32_e32 v219, v219, v215
	v_mul_f32_e32 v220, v220, v216
	v_mul_f32_e32 v221, v221, v217
	v_max_f32_e32 v210, 0, v148
	v_max_f32_e32 v211, 0, v149
	v_max_f32_e32 v212, 0, v150
	v_max_f32_e32 v213, 0, v151
	v_fma_f32 v222, -|v148|, v218, v210
	v_fma_f32 v223, -|v149|, v219, v211
	v_fma_f32 v224, -|v150|, v220, v212
	v_fma_f32 v225, -|v151|, v221, v213
	v_mul_f32_e32 v144, v144, v222
	v_mul_f32_e32 v145, v145, v223
	v_mul_f32_e32 v146, v146, v224
	v_mul_f32_e32 v147, v147, v225
	v_cvt_pk_bf16_f32 v152, v144, v145
	v_cvt_pk_bf16_f32 v153, v146, v147
	v_cndmask_b32_e64 v104, v76, v116, s[16:17]
	v_cndmask_b32_e64 v105, v77, v117, s[16:17]
	v_cndmask_b32_e64 v106, v78, v118, s[16:17]
	v_cndmask_b32_e64 v107, v79, v119, s[16:17]
	v_cndmask_b32_e64 v108, v76, v68, s[4:5]
	v_cndmask_b32_e64 v109, v77, v69, s[4:5]
	v_cndmask_b32_e64 v110, v78, v70, s[4:5]
	v_cndmask_b32_e64 v111, v79, v71, s[4:5]
	v_mul_f32_dpp v144, v104, v160 row_ror:1 row_mask:0xf bank_mask:0xf
	v_mul_f32_dpp v145, v105, v161 row_ror:1 row_mask:0xf bank_mask:0xf
	v_mul_f32_dpp v146, v106, v162 row_ror:1 row_mask:0xf bank_mask:0xf
	v_mul_f32_dpp v147, v107, v163 row_ror:1 row_mask:0xf bank_mask:0xf
	v_fmac_f32_e32 v144, v76, v164
	v_fmac_f32_e32 v145, v77, v165
	v_fmac_f32_e32 v146, v78, v166
	v_fmac_f32_e32 v147, v79, v167
	v_fmac_f32_dpp v144, v108, v168 row_ror:15 row_mask:0xf bank_mask:0xf
	v_fmac_f32_dpp v145, v109, v169 row_ror:15 row_mask:0xf bank_mask:0xf
	v_fmac_f32_dpp v146, v110, v170 row_ror:15 row_mask:0xf bank_mask:0xf
	v_fmac_f32_dpp v147, v111, v171 row_ror:15 row_mask:0xf bank_mask:0xf
	v_add_f32_e32 v144, v172, v144
	v_add_f32_e32 v145, v173, v145
	v_add_f32_e32 v146, v174, v146
	v_add_f32_e32 v147, v175, v147
	v_cndmask_b32_e64 v104, v72, v112, s[16:17]
	v_cndmask_b32_e64 v105, v73, v113, s[16:17]
	v_cndmask_b32_e64 v106, v74, v114, s[16:17]
	v_cndmask_b32_e64 v107, v75, v115, s[16:17]
	v_cndmask_b32_e64 v108, v72, v64, s[4:5]
	v_cndmask_b32_e64 v109, v73, v65, s[4:5]
	v_cndmask_b32_e64 v110, v74, v66, s[4:5]
	v_cndmask_b32_e64 v111, v75, v67, s[4:5]
	v_mul_f32_dpp v148, v104, v182 row_ror:1 row_mask:0xf bank_mask:0xf
	v_mul_f32_dpp v149, v105, v183 row_ror:1 row_mask:0xf bank_mask:0xf
	v_mul_f32_dpp v150, v106, v184 row_ror:1 row_mask:0xf bank_mask:0xf
	v_mul_f32_dpp v151, v107, v185 row_ror:1 row_mask:0xf bank_mask:0xf
	v_fmac_f32_e32 v148, v72, v186
	v_fmac_f32_e32 v149, v73, v187
	v_fmac_f32_e32 v150, v74, v188
	v_fmac_f32_e32 v151, v75, v189
	v_fmac_f32_dpp v148, v108, v190 row_ror:15 row_mask:0xf bank_mask:0xf
	v_fmac_f32_dpp v149, v109, v191 row_ror:15 row_mask:0xf bank_mask:0xf
	v_fmac_f32_dpp v150, v110, v192 row_ror:15 row_mask:0xf bank_mask:0xf
	v_fmac_f32_dpp v151, v111, v193 row_ror:15 row_mask:0xf bank_mask:0xf
	v_add_f32_e32 v148, v194, v148
	v_add_f32_e32 v149, v195, v149
	v_add_f32_e32 v150, v196, v150
	v_add_f32_e32 v151, v197, v151
	v_fma_f32 v210, |v148|, s10, 1.0
	v_fma_f32 v211, |v149|, s10, 1.0
	v_fma_f32 v212, |v150|, s10, 1.0
	v_fma_f32 v213, |v151|, s10, 1.0
	v_rcp_f32_e32 v210, v210
	v_rcp_f32_e32 v211, v211
	v_rcp_f32_e32 v212, v212
	v_rcp_f32_e32 v213, v213
	v_mul_f32_e32 v218, v148, v148
	v_mul_f32_e32 v219, v149, v149
	v_mul_f32_e32 v220, v150, v150
	v_mul_f32_e32 v221, v151, v151
	v_fmaak_f32 v214, v210, v134, 0xbf3a00e3
	v_fmaak_f32 v215, v211, v134, 0xbf3a00e3
	v_fmaak_f32 v216, v212, v134, 0xbf3a00e3
	v_fmaak_f32 v217, v213, v134, 0xbf3a00e3
	v_fmaak_f32 v214, v214, v210, 0x3f35f0e3
	v_fmaak_f32 v215, v215, v211, 0x3f35f0e3
	v_fmaak_f32 v216, v216, v212, 0x3f35f0e3
	v_fmaak_f32 v217, v217, v213, 0x3f35f0e3
	v_fmaak_f32 v214, v214, v210, 0xbe11a98e
	v_fmaak_f32 v215, v215, v211, 0xbe11a98e
	v_fmaak_f32 v216, v216, v212, 0xbe11a98e
	v_fmaak_f32 v217, v217, v213, 0xbe11a98e
	v_fmaak_f32 v214, v214, v210, 0x3e027906
	v_fmaak_f32 v215, v215, v211, 0x3e027906
	v_fmaak_f32 v216, v216, v212, 0x3e027906
	v_fmaak_f32 v217, v217, v213, 0x3e027906
	v_mul_f32_e32 v214, v214, v210
	v_mul_f32_e32 v215, v215, v211
	v_mul_f32_e32 v216, v216, v212
	v_mul_f32_e32 v217, v217, v213
	v_mul_f32_e32 v218, 0xbf38aa3b, v218
	v_mul_f32_e32 v219, 0xbf38aa3b, v219
	v_mul_f32_e32 v220, 0xbf38aa3b, v220
	v_mul_f32_e32 v221, 0xbf38aa3b, v221
	v_exp_f32_e32 v218, v218
	v_exp_f32_e32 v219, v219
	v_exp_f32_e32 v220, v220
	v_exp_f32_e32 v221, v221
	v_mul_f32_e32 v218, v218, v214
	v_mul_f32_e32 v219, v219, v215
	v_mul_f32_e32 v220, v220, v216
	v_mul_f32_e32 v221, v221, v217
	v_max_f32_e32 v210, 0, v148
	v_max_f32_e32 v211, 0, v149
	v_max_f32_e32 v212, 0, v150
	v_max_f32_e32 v213, 0, v151
	v_fma_f32 v222, -|v148|, v218, v210
	v_fma_f32 v223, -|v149|, v219, v211
	v_fma_f32 v224, -|v150|, v220, v212
	v_fma_f32 v225, -|v151|, v221, v213
	v_mul_f32_e32 v144, v144, v222
	v_mul_f32_e32 v145, v145, v223
	v_mul_f32_e32 v146, v146, v224
	v_mul_f32_e32 v147, v147, v225
	v_cvt_pk_bf16_f32 v140, v144, v145
	v_cvt_pk_bf16_f32 v141, v146, v147
	s_waitcnt lgkmcnt(0)
	v_cndmask_b32_e64 v104, v68, v76, s[16:17]
	v_cndmask_b32_e64 v105, v69, v77, s[16:17]
	v_cndmask_b32_e64 v106, v70, v78, s[16:17]
	v_cndmask_b32_e64 v107, v71, v79, s[16:17]
	v_cndmask_b32_e64 v108, v68, v120, s[4:5]
	v_cndmask_b32_e64 v109, v69, v121, s[4:5]
	v_cndmask_b32_e64 v110, v70, v122, s[4:5]
	v_cndmask_b32_e64 v111, v71, v123, s[4:5]
	v_mul_f32_dpp v144, v104, v160 row_ror:1 row_mask:0xf bank_mask:0xf
	v_mul_f32_dpp v145, v105, v161 row_ror:1 row_mask:0xf bank_mask:0xf
	v_mul_f32_dpp v146, v106, v162 row_ror:1 row_mask:0xf bank_mask:0xf
	v_mul_f32_dpp v147, v107, v163 row_ror:1 row_mask:0xf bank_mask:0xf
	v_fmac_f32_e32 v144, v68, v164
	v_fmac_f32_e32 v145, v69, v165
	v_fmac_f32_e32 v146, v70, v166
	v_fmac_f32_e32 v147, v71, v167
	v_fmac_f32_dpp v144, v108, v168 row_ror:15 row_mask:0xf bank_mask:0xf
	v_fmac_f32_dpp v145, v109, v169 row_ror:15 row_mask:0xf bank_mask:0xf
	v_fmac_f32_dpp v146, v110, v170 row_ror:15 row_mask:0xf bank_mask:0xf
	v_fmac_f32_dpp v147, v111, v171 row_ror:15 row_mask:0xf bank_mask:0xf
	v_add_f32_e32 v144, v172, v144
	v_add_f32_e32 v145, v173, v145
	v_add_f32_e32 v146, v174, v146
	v_add_f32_e32 v147, v175, v147
	v_cndmask_b32_e64 v104, v64, v72, s[16:17]
	v_cndmask_b32_e64 v105, v65, v73, s[16:17]
	v_cndmask_b32_e64 v106, v66, v74, s[16:17]
	v_cndmask_b32_e64 v107, v67, v75, s[16:17]
	v_cndmask_b32_e64 v108, v64, v124, s[4:5]
	v_cndmask_b32_e64 v109, v65, v125, s[4:5]
	v_cndmask_b32_e64 v110, v66, v126, s[4:5]
	v_cndmask_b32_e64 v111, v67, v127, s[4:5]
	v_mul_f32_dpp v148, v104, v182 row_ror:1 row_mask:0xf bank_mask:0xf
	v_mul_f32_dpp v149, v105, v183 row_ror:1 row_mask:0xf bank_mask:0xf
	v_mul_f32_dpp v150, v106, v184 row_ror:1 row_mask:0xf bank_mask:0xf
	v_mul_f32_dpp v151, v107, v185 row_ror:1 row_mask:0xf bank_mask:0xf
	v_fmac_f32_e32 v148, v64, v186
	v_fmac_f32_e32 v149, v65, v187
	v_fmac_f32_e32 v150, v66, v188
	v_fmac_f32_e32 v151, v67, v189
	v_fmac_f32_dpp v148, v108, v190 row_ror:15 row_mask:0xf bank_mask:0xf
	v_fmac_f32_dpp v149, v109, v191 row_ror:15 row_mask:0xf bank_mask:0xf
	v_fmac_f32_dpp v150, v110, v192 row_ror:15 row_mask:0xf bank_mask:0xf
	v_fmac_f32_dpp v151, v111, v193 row_ror:15 row_mask:0xf bank_mask:0xf
	v_add_f32_e32 v148, v194, v148
	v_add_f32_e32 v149, v195, v149
	v_add_f32_e32 v150, v196, v150
	v_add_f32_e32 v151, v197, v151
	v_fma_f32 v210, |v148|, s10, 1.0
	v_fma_f32 v211, |v149|, s10, 1.0
	v_fma_f32 v212, |v150|, s10, 1.0
	v_fma_f32 v213, |v151|, s10, 1.0
	v_rcp_f32_e32 v210, v210
	v_rcp_f32_e32 v211, v211
	v_rcp_f32_e32 v212, v212
	v_rcp_f32_e32 v213, v213
	v_mul_f32_e32 v218, v148, v148
	v_mul_f32_e32 v219, v149, v149
	v_mul_f32_e32 v220, v150, v150
	v_mul_f32_e32 v221, v151, v151
	v_fmaak_f32 v214, v210, v134, 0xbf3a00e3
	v_fmaak_f32 v215, v211, v134, 0xbf3a00e3
	v_fmaak_f32 v216, v212, v134, 0xbf3a00e3
	v_fmaak_f32 v217, v213, v134, 0xbf3a00e3
	v_fmaak_f32 v214, v214, v210, 0x3f35f0e3
	v_fmaak_f32 v215, v215, v211, 0x3f35f0e3
	v_fmaak_f32 v216, v216, v212, 0x3f35f0e3
	v_fmaak_f32 v217, v217, v213, 0x3f35f0e3
	v_fmaak_f32 v214, v214, v210, 0xbe11a98e
	v_fmaak_f32 v215, v215, v211, 0xbe11a98e
	v_fmaak_f32 v216, v216, v212, 0xbe11a98e
	v_fmaak_f32 v217, v217, v213, 0xbe11a98e
	v_fmaak_f32 v214, v214, v210, 0x3e027906
	v_fmaak_f32 v215, v215, v211, 0x3e027906
	v_fmaak_f32 v216, v216, v212, 0x3e027906
	v_fmaak_f32 v217, v217, v213, 0x3e027906
	v_mul_f32_e32 v214, v214, v210
	v_mul_f32_e32 v215, v215, v211
	v_mul_f32_e32 v216, v216, v212
	v_mul_f32_e32 v217, v217, v213
	v_mul_f32_e32 v218, 0xbf38aa3b, v218
	v_mul_f32_e32 v219, 0xbf38aa3b, v219
	v_mul_f32_e32 v220, 0xbf38aa3b, v220
	v_mul_f32_e32 v221, 0xbf38aa3b, v221
	v_exp_f32_e32 v218, v218
	v_exp_f32_e32 v219, v219
	v_exp_f32_e32 v220, v220
	v_exp_f32_e32 v221, v221
	v_mul_f32_e32 v218, v218, v214
	v_mul_f32_e32 v219, v219, v215
	v_mul_f32_e32 v220, v220, v216
	v_mul_f32_e32 v221, v221, v217
	v_max_f32_e32 v210, 0, v148
	v_max_f32_e32 v211, 0, v149
	v_max_f32_e32 v212, 0, v150
	v_max_f32_e32 v213, 0, v151
	v_fma_f32 v222, -|v148|, v218, v210
	v_fma_f32 v223, -|v149|, v219, v211
	v_fma_f32 v224, -|v150|, v220, v212
	v_fma_f32 v225, -|v151|, v221, v213
	v_mul_f32_e32 v144, v144, v222
	v_mul_f32_e32 v145, v145, v223
	v_mul_f32_e32 v146, v146, v224
	v_mul_f32_e32 v147, v147, v225
	v_cvt_pk_bf16_f32 v136, v144, v145
	v_cvt_pk_bf16_f32 v137, v146, v147
	s_lshl_b32 s2, s8, 7
	s_or_b32 s2, s2, s53
	v_lshl_add_u32 v226, v207, 2, s2
	v_lshlrev_b32_e32 v226, 2, v226
	v_add_u32_e32 v210, 0x5800, v226
	v_add_u32_e32 v211, 0xb000, v226
	v_add_u32_e32 v212, 0x2c00, v226
	v_add_u32_e32 v213, 0x8400, v226
	v_add_u32_e32 v214, 0xdc00, v226
	global_load_dwordx4 v[160:163], v226, s[70:71] offset:64
	global_load_dwordx4 v[164:167], v210, s[70:71] offset:64
	global_load_dwordx4 v[168:171], v211, s[70:71] offset:64
	global_load_dwordx4 v[182:185], v212, s[70:71] offset:64
	global_load_dwordx4 v[186:189], v213, s[70:71] offset:64
	global_load_dwordx4 v[190:193], v214, s[70:71] offset:64
	global_load_dwordx4 v[172:175], v226, s[58:59] offset:64
	global_load_dwordx4 v[194:197], v212, s[58:59] offset:64
	s_and_b64 vcc, exec, s[6:7]
	s_cbranch_vccz .Lp6e_z4
	ds_read_b128 v[120:123], v228 offset:64
	ds_read_b128 v[124:127], v228 offset:192
	s_branch .Lp6e_d4

.Lp6e_d4:
	s_waitcnt lgkmcnt(0)
	s_waitcnt vmcnt(0)
	v_cndmask_b32_e64 v104, v60, v120, s[16:17]
	v_cndmask_b32_e64 v105, v61, v121, s[16:17]
	v_cndmask_b32_e64 v106, v62, v122, s[16:17]
	v_cndmask_b32_e64 v107, v63, v123, s[16:17]
	v_cndmask_b32_e64 v108, v60, v52, s[4:5]
	v_cndmask_b32_e64 v109, v61, v53, s[4:5]
	v_cndmask_b32_e64 v110, v62, v54, s[4:5]
	v_cndmask_b32_e64 v111, v63, v55, s[4:5]
	v_mul_f32_dpp v144, v104, v160 row_ror:1 row_mask:0xf bank_mask:0xf
	v_mul_f32_dpp v145, v105, v161 row_ror:1 row_mask:0xf bank_mask:0xf
	v_mul_f32_dpp v146, v106, v162 row_ror:1 row_mask:0xf bank_mask:0xf
	v_mul_f32_dpp v147, v107, v163 row_ror:1 row_mask:0xf bank_mask:0xf
	v_fmac_f32_e32 v144, v60, v164
	v_fmac_f32_e32 v145, v61, v165
	v_fmac_f32_e32 v146, v62, v166
	v_fmac_f32_e32 v147, v63, v167
	v_fmac_f32_dpp v144, v108, v168 row_ror:15 row_mask:0xf bank_mask:0xf
	v_fmac_f32_dpp v145, v109, v169 row_ror:15 row_mask:0xf bank_mask:0xf
	v_fmac_f32_dpp v146, v110, v170 row_ror:15 row_mask:0xf bank_mask:0xf
	v_fmac_f32_dpp v147, v111, v171 row_ror:15 row_mask:0xf bank_mask:0xf
	v_add_f32_e32 v144, v172, v144
	v_add_f32_e32 v145, v173, v145
	v_add_f32_e32 v146, v174, v146
	v_add_f32_e32 v147, v175, v147
	v_cndmask_b32_e64 v104, v56, v124, s[16:17]
	v_cndmask_b32_e64 v105, v57, v125, s[16:17]
	v_cndmask_b32_e64 v106, v58, v126, s[16:17]
	v_cndmask_b32_e64 v107, v59, v127, s[16:17]
	v_cndmask_b32_e64 v108, v56, v48, s[4:5]
	v_cndmask_b32_e64 v109, v57, v49, s[4:5]
	v_cndmask_b32_e64 v110, v58, v50, s[4:5]
	v_cndmask_b32_e64 v111, v59, v51, s[4:5]
	v_mul_f32_dpp v148, v104, v182 row_ror:1 row_mask:0xf bank_mask:0xf
	v_mul_f32_dpp v149, v105, v183 row_ror:1 row_mask:0xf bank_mask:0xf
	v_mul_f32_dpp v150, v106, v184 row_ror:1 row_mask:0xf bank_mask:0xf
	v_mul_f32_dpp v151, v107, v185 row_ror:1 row_mask:0xf bank_mask:0xf
	v_fmac_f32_e32 v148, v56, v186
	v_fmac_f32_e32 v149, v57, v187
	v_fmac_f32_e32 v150, v58, v188
	v_fmac_f32_e32 v151, v59, v189
	v_fmac_f32_dpp v148, v108, v190 row_ror:15 row_mask:0xf bank_mask:0xf
	v_fmac_f32_dpp v149, v109, v191 row_ror:15 row_mask:0xf bank_mask:0xf
	v_fmac_f32_dpp v150, v110, v192 row_ror:15 row_mask:0xf bank_mask:0xf
	v_fmac_f32_dpp v151, v111, v193 row_ror:15 row_mask:0xf bank_mask:0xf
	v_add_f32_e32 v148, v194, v148
	v_add_f32_e32 v149, v195, v149
	v_add_f32_e32 v150, v196, v150
	v_add_f32_e32 v151, v197, v151
	v_fma_f32 v210, |v148|, s10, 1.0
	v_fma_f32 v211, |v149|, s10, 1.0
	v_fma_f32 v212, |v150|, s10, 1.0
	v_fma_f32 v213, |v151|, s10, 1.0
	v_rcp_f32_e32 v210, v210
	v_rcp_f32_e32 v211, v211
	v_rcp_f32_e32 v212, v212
	v_rcp_f32_e32 v213, v213
	v_mul_f32_e32 v218, v148, v148
	v_mul_f32_e32 v219, v149, v149
	v_mul_f32_e32 v220, v150, v150
	v_mul_f32_e32 v221, v151, v151
	v_fmaak_f32 v214, v210, v134, 0xbf3a00e3
	v_fmaak_f32 v215, v211, v134, 0xbf3a00e3
	v_fmaak_f32 v216, v212, v134, 0xbf3a00e3
	v_fmaak_f32 v217, v213, v134, 0xbf3a00e3
	v_fmaak_f32 v214, v214, v210, 0x3f35f0e3
	v_fmaak_f32 v215, v215, v211, 0x3f35f0e3
	v_fmaak_f32 v216, v216, v212, 0x3f35f0e3
	v_fmaak_f32 v217, v217, v213, 0x3f35f0e3
	v_fmaak_f32 v214, v214, v210, 0xbe11a98e
	v_fmaak_f32 v215, v215, v211, 0xbe11a98e
	v_fmaak_f32 v216, v216, v212, 0xbe11a98e
	v_fmaak_f32 v217, v217, v213, 0xbe11a98e
	v_fmaak_f32 v214, v214, v210, 0x3e027906
	v_fmaak_f32 v215, v215, v211, 0x3e027906
	v_fmaak_f32 v216, v216, v212, 0x3e027906
	v_fmaak_f32 v217, v217, v213, 0x3e027906
	v_mul_f32_e32 v214, v214, v210
	v_mul_f32_e32 v215, v215, v211
	v_mul_f32_e32 v216, v216, v212
	v_mul_f32_e32 v217, v217, v213
	v_mul_f32_e32 v218, 0xbf38aa3b, v218
	v_mul_f32_e32 v219, 0xbf38aa3b, v219
	v_mul_f32_e32 v220, 0xbf38aa3b, v220
	v_mul_f32_e32 v221, 0xbf38aa3b, v221
	v_exp_f32_e32 v218, v218
	v_exp_f32_e32 v219, v219
	v_exp_f32_e32 v220, v220
	v_exp_f32_e32 v221, v221
	v_mul_f32_e32 v218, v218, v214
	v_mul_f32_e32 v219, v219, v215
	v_mul_f32_e32 v220, v220, v216
	v_mul_f32_e32 v221, v221, v217
	v_max_f32_e32 v210, 0, v148
	v_max_f32_e32 v211, 0, v149
	v_max_f32_e32 v212, 0, v150
	v_max_f32_e32 v213, 0, v151
	v_fma_f32 v222, -|v148|, v218, v210
	v_fma_f32 v223, -|v149|, v219, v211
	v_fma_f32 v224, -|v150|, v220, v212
	v_fma_f32 v225, -|v151|, v221, v213
	v_mul_f32_e32 v144, v144, v222
	v_mul_f32_e32 v145, v145, v223
	v_mul_f32_e32 v146, v146, v224
	v_mul_f32_e32 v147, v147, v225
	v_cvt_pk_bf16_f32 v204, v144, v145
	v_cvt_pk_bf16_f32 v205, v146, v147
	s_mov_b32 s14, 0x0
	v_lshl_add_u64 v[198:199], v[132:133], 0, s[14:15]
	v_permlane16_swap_b32_e32 v202, v204
	v_permlane16_swap_b32_e32 v203, v205
	s_and_b64 s[18:19], s[4:5], s[66:67]
	s_andn2_b64 s[18:19], exec, s[18:19]
	s_and_saveexec_b64 s[20:21], s[18:19]
	global_store_dwordx4 v[198:199], v[202:205], off
	s_mov_b64 exec, s[20:21]
	ds_read_b128 v[120:123], v135 offset:576
	ds_read_b128 v[124:127], v135 offset:704
	v_cndmask_b32_e64 v104, v52, v60, s[16:17]
	v_cndmask_b32_e64 v105, v53, v61, s[16:17]
	v_cndmask_b32_e64 v106, v54, v62, s[16:17]
	v_cndmask_b32_e64 v107, v55, v63, s[16:17]
	v_cndmask_b32_e64 v108, v52, v44, s[4:5]
	v_cndmask_b32_e64 v109, v53, v45, s[4:5]
	v_cndmask_b32_e64 v110, v54, v46, s[4:5]
	v_cndmask_b32_e64 v111, v55, v47, s[4:5]
	v_mul_f32_dpp v144, v104, v160 row_ror:1 row_mask:0xf bank_mask:0xf
	v_mul_f32_dpp v145, v105, v161 row_ror:1 row_mask:0xf bank_mask:0xf
	v_mul_f32_dpp v146, v106, v162 row_ror:1 row_mask:0xf bank_mask:0xf
	v_mul_f32_dpp v147, v107, v163 row_ror:1 row_mask:0xf bank_mask:0xf
	v_fmac_f32_e32 v144, v52, v164
	v_fmac_f32_e32 v145, v53, v165
	v_fmac_f32_e32 v146, v54, v166
	v_fmac_f32_e32 v147, v55, v167
	v_fmac_f32_dpp v144, v108, v168 row_ror:15 row_mask:0xf bank_mask:0xf
	v_fmac_f32_dpp v145, v109, v169 row_ror:15 row_mask:0xf bank_mask:0xf
	v_fmac_f32_dpp v146, v110, v170 row_ror:15 row_mask:0xf bank_mask:0xf
	v_fmac_f32_dpp v147, v111, v171 row_ror:15 row_mask:0xf bank_mask:0xf
	v_add_f32_e32 v144, v172, v144
	v_add_f32_e32 v145, v173, v145
	v_add_f32_e32 v146, v174, v146
	v_add_f32_e32 v147, v175, v147
	v_cndmask_b32_e64 v104, v48, v56, s[16:17]
	v_cndmask_b32_e64 v105, v49, v57, s[16:17]
	v_cndmask_b32_e64 v106, v50, v58, s[16:17]
	v_cndmask_b32_e64 v107, v51, v59, s[16:17]
	v_cndmask_b32_e64 v108, v48, v40, s[4:5]
	v_cndmask_b32_e64 v109, v49, v41, s[4:5]
	v_cndmask_b32_e64 v110, v50, v42, s[4:5]
	v_cndmask_b32_e64 v111, v51, v43, s[4:5]
	v_mul_f32_dpp v148, v104, v182 row_ror:1 row_mask:0xf bank_mask:0xf
	v_mul_f32_dpp v149, v105, v183 row_ror:1 row_mask:0xf bank_mask:0xf
	v_mul_f32_dpp v150, v106, v184 row_ror:1 row_mask:0xf bank_mask:0xf
	v_mul_f32_dpp v151, v107, v185 row_ror:1 row_mask:0xf bank_mask:0xf
	v_fmac_f32_e32 v148, v48, v186
	v_fmac_f32_e32 v149, v49, v187
	v_fmac_f32_e32 v150, v50, v188
	v_fmac_f32_e32 v151, v51, v189
	v_fmac_f32_dpp v148, v108, v190 row_ror:15 row_mask:0xf bank_mask:0xf
	v_fmac_f32_dpp v149, v109, v191 row_ror:15 row_mask:0xf bank_mask:0xf
	v_fmac_f32_dpp v150, v110, v192 row_ror:15 row_mask:0xf bank_mask:0xf
	v_fmac_f32_dpp v151, v111, v193 row_ror:15 row_mask:0xf bank_mask:0xf
	v_add_f32_e32 v148, v194, v148
	v_add_f32_e32 v149, v195, v149
	v_add_f32_e32 v150, v196, v150
	v_add_f32_e32 v151, v197, v151
	v_fma_f32 v210, |v148|, s10, 1.0
	v_fma_f32 v211, |v149|, s10, 1.0
	v_fma_f32 v212, |v150|, s10, 1.0
	v_fma_f32 v213, |v151|, s10, 1.0
	v_rcp_f32_e32 v210, v210
	v_rcp_f32_e32 v211, v211
	v_rcp_f32_e32 v212, v212
	v_rcp_f32_e32 v213, v213
	v_mul_f32_e32 v218, v148, v148
	v_mul_f32_e32 v219, v149, v149
	v_mul_f32_e32 v220, v150, v150
	v_mul_f32_e32 v221, v151, v151
	v_fmaak_f32 v214, v210, v134, 0xbf3a00e3
	v_fmaak_f32 v215, v211, v134, 0xbf3a00e3
	v_fmaak_f32 v216, v212, v134, 0xbf3a00e3
	v_fmaak_f32 v217, v213, v134, 0xbf3a00e3
	v_fmaak_f32 v214, v214, v210, 0x3f35f0e3
	v_fmaak_f32 v215, v215, v211, 0x3f35f0e3
	v_fmaak_f32 v216, v216, v212, 0x3f35f0e3
	v_fmaak_f32 v217, v217, v213, 0x3f35f0e3
	v_fmaak_f32 v214, v214, v210, 0xbe11a98e
	v_fmaak_f32 v215, v215, v211, 0xbe11a98e
	v_fmaak_f32 v216, v216, v212, 0xbe11a98e
	v_fmaak_f32 v217, v217, v213, 0xbe11a98e
	v_fmaak_f32 v214, v214, v210, 0x3e027906
	v_fmaak_f32 v215, v215, v211, 0x3e027906
	v_fmaak_f32 v216, v216, v212, 0x3e027906
	v_fmaak_f32 v217, v217, v213, 0x3e027906
	v_mul_f32_e32 v214, v214, v210
	v_mul_f32_e32 v215, v215, v211
	v_mul_f32_e32 v216, v216, v212
	v_mul_f32_e32 v217, v217, v213
	v_mul_f32_e32 v218, 0xbf38aa3b, v218
	v_mul_f32_e32 v219, 0xbf38aa3b, v219
	v_mul_f32_e32 v220, 0xbf38aa3b, v220
	v_mul_f32_e32 v221, 0xbf38aa3b, v221
	v_exp_f32_e32 v218, v218
	v_exp_f32_e32 v219, v219
	v_exp_f32_e32 v220, v220
	v_exp_f32_e32 v221, v221
	v_mul_f32_e32 v218, v218, v214
	v_mul_f32_e32 v219, v219, v215
	v_mul_f32_e32 v220, v220, v216
	v_mul_f32_e32 v221, v221, v217
	v_max_f32_e32 v210, 0, v148
	v_max_f32_e32 v211, 0, v149
	v_max_f32_e32 v212, 0, v150
	v_max_f32_e32 v213, 0, v151
	v_fma_f32 v222, -|v148|, v218, v210
	v_fma_f32 v223, -|v149|, v219, v211
	v_fma_f32 v224, -|v150|, v220, v212
	v_fma_f32 v225, -|v151|, v221, v213
	v_mul_f32_e32 v144, v144, v222
	v_mul_f32_e32 v145, v145, v223
	v_mul_f32_e32 v146, v146, v224
	v_mul_f32_e32 v147, v147, v225
	v_cvt_pk_bf16_f32 v130, v144, v145
	v_cvt_pk_bf16_f32 v131, v146, v147
	s_mov_b32 s14, 0x16000
	v_lshl_add_u64 v[198:199], v[132:133], 0, s[14:15]
	v_permlane16_swap_b32_e32 v128, v130
	v_permlane16_swap_b32_e32 v129, v131
	global_store_dwordx4 v[198:199], v[128:131], off
	v_cndmask_b32_e64 v104, v44, v52, s[16:17]
	v_cndmask_b32_e64 v105, v45, v53, s[16:17]
	v_cndmask_b32_e64 v106, v46, v54, s[16:17]
	v_cndmask_b32_e64 v107, v47, v55, s[16:17]
	v_cndmask_b32_e64 v108, v44, v84, s[4:5]
	v_cndmask_b32_e64 v109, v45, v85, s[4:5]
	v_cndmask_b32_e64 v110, v46, v86, s[4:5]
	v_cndmask_b32_e64 v111, v47, v87, s[4:5]
	v_mul_f32_dpp v144, v104, v160 row_ror:1 row_mask:0xf bank_mask:0xf
	v_mul_f32_dpp v145, v105, v161 row_ror:1 row_mask:0xf bank_mask:0xf
	v_mul_f32_dpp v146, v106, v162 row_ror:1 row_mask:0xf bank_mask:0xf
	v_mul_f32_dpp v147, v107, v163 row_ror:1 row_mask:0xf bank_mask:0xf
	v_fmac_f32_e32 v144, v44, v164
	v_fmac_f32_e32 v145, v45, v165
	v_fmac_f32_e32 v146, v46, v166
	v_fmac_f32_e32 v147, v47, v167
	v_fmac_f32_dpp v144, v108, v168 row_ror:15 row_mask:0xf bank_mask:0xf
	v_fmac_f32_dpp v145, v109, v169 row_ror:15 row_mask:0xf bank_mask:0xf
	v_fmac_f32_dpp v146, v110, v170 row_ror:15 row_mask:0xf bank_mask:0xf
	v_fmac_f32_dpp v147, v111, v171 row_ror:15 row_mask:0xf bank_mask:0xf
	v_add_f32_e32 v144, v172, v144
	v_add_f32_e32 v145, v173, v145
	v_add_f32_e32 v146, v174, v146
	v_add_f32_e32 v147, v175, v147
	v_cndmask_b32_e64 v104, v40, v48, s[16:17]
	v_cndmask_b32_e64 v105, v41, v49, s[16:17]
	v_cndmask_b32_e64 v106, v42, v50, s[16:17]
	v_cndmask_b32_e64 v107, v43, v51, s[16:17]
	v_cndmask_b32_e64 v108, v40, v32, s[4:5]
	v_cndmask_b32_e64 v109, v41, v33, s[4:5]
	v_cndmask_b32_e64 v110, v42, v34, s[4:5]
	v_cndmask_b32_e64 v111, v43, v35, s[4:5]
	v_mul_f32_dpp v148, v104, v182 row_ror:1 row_mask:0xf bank_mask:0xf
	v_mul_f32_dpp v149, v105, v183 row_ror:1 row_mask:0xf bank_mask:0xf
	v_mul_f32_dpp v150, v106, v184 row_ror:1 row_mask:0xf bank_mask:0xf
	v_mul_f32_dpp v151, v107, v185 row_ror:1 row_mask:0xf bank_mask:0xf
	v_fmac_f32_e32 v148, v40, v186
	v_fmac_f32_e32 v149, v41, v187
	v_fmac_f32_e32 v150, v42, v188
	v_fmac_f32_e32 v151, v43, v189
	v_fmac_f32_dpp v148, v108, v190 row_ror:15 row_mask:0xf bank_mask:0xf
	v_fmac_f32_dpp v149, v109, v191 row_ror:15 row_mask:0xf bank_mask:0xf
	v_fmac_f32_dpp v150, v110, v192 row_ror:15 row_mask:0xf bank_mask:0xf
	v_fmac_f32_dpp v151, v111, v193 row_ror:15 row_mask:0xf bank_mask:0xf
	v_add_f32_e32 v148, v194, v148
	v_add_f32_e32 v149, v195, v149
	v_add_f32_e32 v150, v196, v150
	v_add_f32_e32 v151, v197, v151
	v_fma_f32 v210, |v148|, s10, 1.0
	v_fma_f32 v211, |v149|, s10, 1.0
	v_fma_f32 v212, |v150|, s10, 1.0
	v_fma_f32 v213, |v151|, s10, 1.0
	v_rcp_f32_e32 v210, v210
	v_rcp_f32_e32 v211, v211
	v_rcp_f32_e32 v212, v212
	v_rcp_f32_e32 v213, v213
	v_mul_f32_e32 v218, v148, v148
	v_mul_f32_e32 v219, v149, v149
	v_mul_f32_e32 v220, v150, v150
	v_mul_f32_e32 v221, v151, v151
	v_fmaak_f32 v214, v210, v134, 0xbf3a00e3
	v_fmaak_f32 v215, v211, v134, 0xbf3a00e3
	v_fmaak_f32 v216, v212, v134, 0xbf3a00e3
	v_fmaak_f32 v217, v213, v134, 0xbf3a00e3
	v_fmaak_f32 v214, v214, v210, 0x3f35f0e3
	v_fmaak_f32 v215, v215, v211, 0x3f35f0e3
	v_fmaak_f32 v216, v216, v212, 0x3f35f0e3
	v_fmaak_f32 v217, v217, v213, 0x3f35f0e3
	v_fmaak_f32 v214, v214, v210, 0xbe11a98e
	v_fmaak_f32 v215, v215, v211, 0xbe11a98e
	v_fmaak_f32 v216, v216, v212, 0xbe11a98e
	v_fmaak_f32 v217, v217, v213, 0xbe11a98e
	v_fmaak_f32 v214, v214, v210, 0x3e027906
	v_fmaak_f32 v215, v215, v211, 0x3e027906
	v_fmaak_f32 v216, v216, v212, 0x3e027906
	v_fmaak_f32 v217, v217, v213, 0x3e027906
	v_mul_f32_e32 v214, v214, v210
	v_mul_f32_e32 v215, v215, v211
	v_mul_f32_e32 v216, v216, v212
	v_mul_f32_e32 v217, v217, v213
	v_mul_f32_e32 v218, 0xbf38aa3b, v218
	v_mul_f32_e32 v219, 0xbf38aa3b, v219
	v_mul_f32_e32 v220, 0xbf38aa3b, v220
	v_mul_f32_e32 v221, 0xbf38aa3b, v221
	v_exp_f32_e32 v218, v218
	v_exp_f32_e32 v219, v219
	v_exp_f32_e32 v220, v220
	v_exp_f32_e32 v221, v221
	v_mul_f32_e32 v218, v218, v214
	v_mul_f32_e32 v219, v219, v215
	v_mul_f32_e32 v220, v220, v216
	v_mul_f32_e32 v221, v221, v217
	v_max_f32_e32 v210, 0, v148
	v_max_f32_e32 v211, 0, v149
	v_max_f32_e32 v212, 0, v150
	v_max_f32_e32 v213, 0, v151
	v_fma_f32 v222, -|v148|, v218, v210
	v_fma_f32 v223, -|v149|, v219, v211
	v_fma_f32 v224, -|v150|, v220, v212
	v_fma_f32 v225, -|v151|, v221, v213
	v_mul_f32_e32 v144, v144, v222
	v_mul_f32_e32 v145, v145, v223
	v_mul_f32_e32 v146, v146, v224
	v_mul_f32_e32 v147, v147, v225
	v_cvt_pk_bf16_f32 v102, v144, v145
	v_cvt_pk_bf16_f32 v103, v146, v147
	s_mov_b32 s14, 0x2c000
	v_lshl_add_u64 v[198:199], v[132:133], 0, s[14:15]
	v_permlane16_swap_b32_e32 v100, v102
	v_permlane16_swap_b32_e32 v101, v103
	global_store_dwordx4 v[198:199], v[100:103], off
	s_waitcnt lgkmcnt(0)
	v_cndmask_b32_e64 v104, v84, v44, s[16:17]
	v_cndmask_b32_e64 v105, v85, v45, s[16:17]
	v_cndmask_b32_e64 v106, v86, v46, s[16:17]
	v_cndmask_b32_e64 v107, v87, v47, s[16:17]
	v_cndmask_b32_e64 v108, v84, v120, s[4:5]
	v_cndmask_b32_e64 v109, v85, v121, s[4:5]
	v_cndmask_b32_e64 v110, v86, v122, s[4:5]
	v_cndmask_b32_e64 v111, v87, v123, s[4:5]
	v_mul_f32_dpp v144, v104, v160 row_ror:1 row_mask:0xf bank_mask:0xf
	v_mul_f32_dpp v145, v105, v161 row_ror:1 row_mask:0xf bank_mask:0xf
	v_mul_f32_dpp v146, v106, v162 row_ror:1 row_mask:0xf bank_mask:0xf
	v_mul_f32_dpp v147, v107, v163 row_ror:1 row_mask:0xf bank_mask:0xf
	v_fmac_f32_e32 v144, v84, v164
	v_fmac_f32_e32 v145, v85, v165
	v_fmac_f32_e32 v146, v86, v166
	v_fmac_f32_e32 v147, v87, v167
	v_fmac_f32_dpp v144, v108, v168 row_ror:15 row_mask:0xf bank_mask:0xf
	v_fmac_f32_dpp v145, v109, v169 row_ror:15 row_mask:0xf bank_mask:0xf
	v_fmac_f32_dpp v146, v110, v170 row_ror:15 row_mask:0xf bank_mask:0xf
	v_fmac_f32_dpp v147, v111, v171 row_ror:15 row_mask:0xf bank_mask:0xf
	v_add_f32_e32 v144, v172, v144
	v_add_f32_e32 v145, v173, v145
	v_add_f32_e32 v146, v174, v146
	v_add_f32_e32 v147, v175, v147
	v_cndmask_b32_e64 v104, v32, v40, s[16:17]
	v_cndmask_b32_e64 v105, v33, v41, s[16:17]
	v_cndmask_b32_e64 v106, v34, v42, s[16:17]
	v_cndmask_b32_e64 v107, v35, v43, s[16:17]
	v_cndmask_b32_e64 v108, v32, v124, s[4:5]
	v_cndmask_b32_e64 v109, v33, v125, s[4:5]
	v_cndmask_b32_e64 v110, v34, v126, s[4:5]
	v_cndmask_b32_e64 v111, v35, v127, s[4:5]
	v_mul_f32_dpp v148, v104, v182 row_ror:1 row_mask:0xf bank_mask:0xf
	v_mul_f32_dpp v149, v105, v183 row_ror:1 row_mask:0xf bank_mask:0xf
	v_mul_f32_dpp v150, v106, v184 row_ror:1 row_mask:0xf bank_mask:0xf
	v_mul_f32_dpp v151, v107, v185 row_ror:1 row_mask:0xf bank_mask:0xf
	v_fmac_f32_e32 v148, v32, v186
	v_fmac_f32_e32 v149, v33, v187
	v_fmac_f32_e32 v150, v34, v188
	v_fmac_f32_e32 v151, v35, v189
	v_fmac_f32_dpp v148, v108, v190 row_ror:15 row_mask:0xf bank_mask:0xf
	v_fmac_f32_dpp v149, v109, v191 row_ror:15 row_mask:0xf bank_mask:0xf
	v_fmac_f32_dpp v150, v110, v192 row_ror:15 row_mask:0xf bank_mask:0xf
	v_fmac_f32_dpp v151, v111, v193 row_ror:15 row_mask:0xf bank_mask:0xf
	v_add_f32_e32 v148, v194, v148
	v_add_f32_e32 v149, v195, v149
	v_add_f32_e32 v150, v196, v150
	v_add_f32_e32 v151, v197, v151
	v_fma_f32 v210, |v148|, s10, 1.0
	v_fma_f32 v211, |v149|, s10, 1.0
	v_fma_f32 v212, |v150|, s10, 1.0
	v_fma_f32 v213, |v151|, s10, 1.0
	v_rcp_f32_e32 v210, v210
	v_rcp_f32_e32 v211, v211
	v_rcp_f32_e32 v212, v212
	v_rcp_f32_e32 v213, v213
	v_mul_f32_e32 v218, v148, v148
	v_mul_f32_e32 v219, v149, v149
	v_mul_f32_e32 v220, v150, v150
	v_mul_f32_e32 v221, v151, v151
	v_fmaak_f32 v214, v210, v134, 0xbf3a00e3
	v_fmaak_f32 v215, v211, v134, 0xbf3a00e3
	v_fmaak_f32 v216, v212, v134, 0xbf3a00e3
	v_fmaak_f32 v217, v213, v134, 0xbf3a00e3
	v_fmaak_f32 v214, v214, v210, 0x3f35f0e3
	v_fmaak_f32 v215, v215, v211, 0x3f35f0e3
	v_fmaak_f32 v216, v216, v212, 0x3f35f0e3
	v_fmaak_f32 v217, v217, v213, 0x3f35f0e3
	v_fmaak_f32 v214, v214, v210, 0xbe11a98e
	v_fmaak_f32 v215, v215, v211, 0xbe11a98e
	v_fmaak_f32 v216, v216, v212, 0xbe11a98e
	v_fmaak_f32 v217, v217, v213, 0xbe11a98e
	v_fmaak_f32 v214, v214, v210, 0x3e027906
	v_fmaak_f32 v215, v215, v211, 0x3e027906
	v_fmaak_f32 v216, v216, v212, 0x3e027906
	v_fmaak_f32 v217, v217, v213, 0x3e027906
	v_mul_f32_e32 v214, v214, v210
	v_mul_f32_e32 v215, v215, v211
	v_mul_f32_e32 v216, v216, v212
	v_mul_f32_e32 v217, v217, v213
	v_mul_f32_e32 v218, 0xbf38aa3b, v218
	v_mul_f32_e32 v219, 0xbf38aa3b, v219
	v_mul_f32_e32 v220, 0xbf38aa3b, v220
	v_mul_f32_e32 v221, 0xbf38aa3b, v221
	v_exp_f32_e32 v218, v218
	v_exp_f32_e32 v219, v219
	v_exp_f32_e32 v220, v220
	v_exp_f32_e32 v221, v221
	v_mul_f32_e32 v218, v218, v214
	v_mul_f32_e32 v219, v219, v215
	v_mul_f32_e32 v220, v220, v216
	v_mul_f32_e32 v221, v221, v217
	v_max_f32_e32 v210, 0, v148
	v_max_f32_e32 v211, 0, v149
	v_max_f32_e32 v212, 0, v150
	v_max_f32_e32 v213, 0, v151
	v_fma_f32 v222, -|v148|, v218, v210
	v_fma_f32 v223, -|v149|, v219, v211
	v_fma_f32 v224, -|v150|, v220, v212
	v_fma_f32 v225, -|v151|, v221, v213
	v_mul_f32_e32 v144, v144, v222
	v_mul_f32_e32 v145, v145, v223
	v_mul_f32_e32 v146, v146, v224
	v_mul_f32_e32 v147, v147, v225
	v_cvt_pk_bf16_f32 v98, v144, v145
	v_cvt_pk_bf16_f32 v99, v146, v147
	s_mov_b32 s14, 0x42000
	v_lshl_add_u64 v[198:199], v[132:133], 0, s[14:15]
	v_permlane16_swap_b32_e32 v96, v98
	v_permlane16_swap_b32_e32 v97, v99
	global_store_dwordx4 v[198:199], v[96:99], off
	ds_read_b128 v[120:123], v228 offset:1088
	ds_read_b128 v[124:127], v228 offset:1216
	s_waitcnt lgkmcnt(0)
	v_cndmask_b32_e64 v104, v28, v120, s[16:17]
	v_cndmask_b32_e64 v105, v29, v121, s[16:17]
	v_cndmask_b32_e64 v106, v30, v122, s[16:17]
	v_cndmask_b32_e64 v107, v31, v123, s[16:17]
	v_cndmask_b32_e64 v108, v28, v20, s[4:5]
	v_cndmask_b32_e64 v109, v29, v21, s[4:5]
	v_cndmask_b32_e64 v110, v30, v22, s[4:5]
	v_cndmask_b32_e64 v111, v31, v23, s[4:5]
	v_mul_f32_dpp v144, v104, v160 row_ror:1 row_mask:0xf bank_mask:0xf
	v_mul_f32_dpp v145, v105, v161 row_ror:1 row_mask:0xf bank_mask:0xf
	v_mul_f32_dpp v146, v106, v162 row_ror:1 row_mask:0xf bank_mask:0xf
	v_mul_f32_dpp v147, v107, v163 row_ror:1 row_mask:0xf bank_mask:0xf
	v_fmac_f32_e32 v144, v28, v164
	v_fmac_f32_e32 v145, v29, v165
	v_fmac_f32_e32 v146, v30, v166
	v_fmac_f32_e32 v147, v31, v167
	v_fmac_f32_dpp v144, v108, v168 row_ror:15 row_mask:0xf bank_mask:0xf
	v_fmac_f32_dpp v145, v109, v169 row_ror:15 row_mask:0xf bank_mask:0xf
	v_fmac_f32_dpp v146, v110, v170 row_ror:15 row_mask:0xf bank_mask:0xf
	v_fmac_f32_dpp v147, v111, v171 row_ror:15 row_mask:0xf bank_mask:0xf
	v_add_f32_e32 v144, v172, v144
	v_add_f32_e32 v145, v173, v145
	v_add_f32_e32 v146, v174, v146
	v_add_f32_e32 v147, v175, v147
	v_cndmask_b32_e64 v104, v24, v124, s[16:17]
	v_cndmask_b32_e64 v105, v25, v125, s[16:17]
	v_cndmask_b32_e64 v106, v26, v126, s[16:17]
	v_cndmask_b32_e64 v107, v27, v127, s[16:17]
	v_cndmask_b32_e64 v108, v24, v16, s[4:5]
	v_cndmask_b32_e64 v109, v25, v17, s[4:5]
	v_cndmask_b32_e64 v110, v26, v18, s[4:5]
	v_cndmask_b32_e64 v111, v27, v19, s[4:5]
	v_mul_f32_dpp v148, v104, v182 row_ror:1 row_mask:0xf bank_mask:0xf
	v_mul_f32_dpp v149, v105, v183 row_ror:1 row_mask:0xf bank_mask:0xf
	v_mul_f32_dpp v150, v106, v184 row_ror:1 row_mask:0xf bank_mask:0xf
	v_mul_f32_dpp v151, v107, v185 row_ror:1 row_mask:0xf bank_mask:0xf
	v_fmac_f32_e32 v148, v24, v186
	v_fmac_f32_e32 v149, v25, v187
	v_fmac_f32_e32 v150, v26, v188
	v_fmac_f32_e32 v151, v27, v189
	v_fmac_f32_dpp v148, v108, v190 row_ror:15 row_mask:0xf bank_mask:0xf
	v_fmac_f32_dpp v149, v109, v191 row_ror:15 row_mask:0xf bank_mask:0xf
	v_fmac_f32_dpp v150, v110, v192 row_ror:15 row_mask:0xf bank_mask:0xf
	v_fmac_f32_dpp v151, v111, v193 row_ror:15 row_mask:0xf bank_mask:0xf
	v_add_f32_e32 v148, v194, v148
	v_add_f32_e32 v149, v195, v149
	v_add_f32_e32 v150, v196, v150
	v_add_f32_e32 v151, v197, v151
	v_fma_f32 v210, |v148|, s10, 1.0
	v_fma_f32 v211, |v149|, s10, 1.0
	v_fma_f32 v212, |v150|, s10, 1.0
	v_fma_f32 v213, |v151|, s10, 1.0
	v_rcp_f32_e32 v210, v210
	v_rcp_f32_e32 v211, v211
	v_rcp_f32_e32 v212, v212
	v_rcp_f32_e32 v213, v213
	v_mul_f32_e32 v218, v148, v148
	v_mul_f32_e32 v219, v149, v149
	v_mul_f32_e32 v220, v150, v150
	v_mul_f32_e32 v221, v151, v151
	v_fmaak_f32 v214, v210, v134, 0xbf3a00e3
	v_fmaak_f32 v215, v211, v134, 0xbf3a00e3
	v_fmaak_f32 v216, v212, v134, 0xbf3a00e3
	v_fmaak_f32 v217, v213, v134, 0xbf3a00e3
	v_fmaak_f32 v214, v214, v210, 0x3f35f0e3
	v_fmaak_f32 v215, v215, v211, 0x3f35f0e3
	v_fmaak_f32 v216, v216, v212, 0x3f35f0e3
	v_fmaak_f32 v217, v217, v213, 0x3f35f0e3
	v_fmaak_f32 v214, v214, v210, 0xbe11a98e
	v_fmaak_f32 v215, v215, v211, 0xbe11a98e
	v_fmaak_f32 v216, v216, v212, 0xbe11a98e
	v_fmaak_f32 v217, v217, v213, 0xbe11a98e
	v_fmaak_f32 v214, v214, v210, 0x3e027906
	v_fmaak_f32 v215, v215, v211, 0x3e027906
	v_fmaak_f32 v216, v216, v212, 0x3e027906
	v_fmaak_f32 v217, v217, v213, 0x3e027906
	v_mul_f32_e32 v214, v214, v210
	v_mul_f32_e32 v215, v215, v211
	v_mul_f32_e32 v216, v216, v212
	v_mul_f32_e32 v217, v217, v213
	v_mul_f32_e32 v218, 0xbf38aa3b, v218
	v_mul_f32_e32 v219, 0xbf38aa3b, v219
	v_mul_f32_e32 v220, 0xbf38aa3b, v220
	v_mul_f32_e32 v221, 0xbf38aa3b, v221
	v_exp_f32_e32 v218, v218
	v_exp_f32_e32 v219, v219
	v_exp_f32_e32 v220, v220
	v_exp_f32_e32 v221, v221
	v_mul_f32_e32 v218, v218, v214
	v_mul_f32_e32 v219, v219, v215
	v_mul_f32_e32 v220, v220, v216
	v_mul_f32_e32 v221, v221, v217
	v_max_f32_e32 v210, 0, v148
	v_max_f32_e32 v211, 0, v149
	v_max_f32_e32 v212, 0, v150
	v_max_f32_e32 v213, 0, v151
	v_fma_f32 v222, -|v148|, v218, v210
	v_fma_f32 v223, -|v149|, v219, v211
	v_fma_f32 v224, -|v150|, v220, v212
	v_fma_f32 v225, -|v151|, v221, v213
	v_mul_f32_e32 v144, v144, v222
	v_mul_f32_e32 v145, v145, v223
	v_mul_f32_e32 v146, v146, v224
	v_mul_f32_e32 v147, v147, v225
	v_cvt_pk_bf16_f32 v158, v144, v145
	v_cvt_pk_bf16_f32 v159, v146, v147
	s_mov_b32 s14, 0xb0000
	v_lshl_add_u64 v[198:199], v[132:133], 0, s[14:15]
	v_permlane16_swap_b32_e32 v156, v158
	v_permlane16_swap_b32_e32 v157, v159
	global_store_dwordx4 v[198:199], v[156:159], off
	s_and_b64 vcc, exec, s[66:67]
	s_cbranch_vccz .Lp6e_z7
	ds_read_b128 v[120:123], v135 offset:1600
	ds_read_b128 v[124:127], v135 offset:1728
	s_branch .Lp6e_d7

.Lp6e_d7:
	v_cndmask_b32_e64 v104, v20, v28, s[16:17]
	v_cndmask_b32_e64 v105, v21, v29, s[16:17]
	v_cndmask_b32_e64 v106, v22, v30, s[16:17]
	v_cndmask_b32_e64 v107, v23, v31, s[16:17]
	v_cndmask_b32_e64 v108, v20, v12, s[4:5]
	v_cndmask_b32_e64 v109, v21, v13, s[4:5]
	v_cndmask_b32_e64 v110, v22, v14, s[4:5]
	v_cndmask_b32_e64 v111, v23, v15, s[4:5]
	v_mul_f32_dpp v144, v104, v160 row_ror:1 row_mask:0xf bank_mask:0xf
	v_mul_f32_dpp v145, v105, v161 row_ror:1 row_mask:0xf bank_mask:0xf
	v_mul_f32_dpp v146, v106, v162 row_ror:1 row_mask:0xf bank_mask:0xf
	v_mul_f32_dpp v147, v107, v163 row_ror:1 row_mask:0xf bank_mask:0xf
	v_fmac_f32_e32 v144, v20, v164
	v_fmac_f32_e32 v145, v21, v165
	v_fmac_f32_e32 v146, v22, v166
	v_fmac_f32_e32 v147, v23, v167
	v_fmac_f32_dpp v144, v108, v168 row_ror:15 row_mask:0xf bank_mask:0xf
	v_fmac_f32_dpp v145, v109, v169 row_ror:15 row_mask:0xf bank_mask:0xf
	v_fmac_f32_dpp v146, v110, v170 row_ror:15 row_mask:0xf bank_mask:0xf
	v_fmac_f32_dpp v147, v111, v171 row_ror:15 row_mask:0xf bank_mask:0xf
	v_add_f32_e32 v144, v172, v144
	v_add_f32_e32 v145, v173, v145
	v_add_f32_e32 v146, v174, v146
	v_add_f32_e32 v147, v175, v147
	v_cndmask_b32_e64 v104, v16, v24, s[16:17]
	v_cndmask_b32_e64 v105, v17, v25, s[16:17]
	v_cndmask_b32_e64 v106, v18, v26, s[16:17]
	v_cndmask_b32_e64 v107, v19, v27, s[16:17]
	v_cndmask_b32_e64 v108, v16, v8, s[4:5]
	v_cndmask_b32_e64 v109, v17, v9, s[4:5]
	v_cndmask_b32_e64 v110, v18, v10, s[4:5]
	v_cndmask_b32_e64 v111, v19, v11, s[4:5]
	v_mul_f32_dpp v148, v104, v182 row_ror:1 row_mask:0xf bank_mask:0xf
	v_mul_f32_dpp v149, v105, v183 row_ror:1 row_mask:0xf bank_mask:0xf
	v_mul_f32_dpp v150, v106, v184 row_ror:1 row_mask:0xf bank_mask:0xf
	v_mul_f32_dpp v151, v107, v185 row_ror:1 row_mask:0xf bank_mask:0xf
	v_fmac_f32_e32 v148, v16, v186
	v_fmac_f32_e32 v149, v17, v187
	v_fmac_f32_e32 v150, v18, v188
	v_fmac_f32_e32 v151, v19, v189
	v_fmac_f32_dpp v148, v108, v190 row_ror:15 row_mask:0xf bank_mask:0xf
	v_fmac_f32_dpp v149, v109, v191 row_ror:15 row_mask:0xf bank_mask:0xf
	v_fmac_f32_dpp v150, v110, v192 row_ror:15 row_mask:0xf bank_mask:0xf
	v_fmac_f32_dpp v151, v111, v193 row_ror:15 row_mask:0xf bank_mask:0xf
	v_add_f32_e32 v148, v194, v148
	v_add_f32_e32 v149, v195, v149
	v_add_f32_e32 v150, v196, v150
	v_add_f32_e32 v151, v197, v151
	v_fma_f32 v210, |v148|, s10, 1.0
	v_fma_f32 v211, |v149|, s10, 1.0
	v_fma_f32 v212, |v150|, s10, 1.0
	v_fma_f32 v213, |v151|, s10, 1.0
	v_rcp_f32_e32 v210, v210
	v_rcp_f32_e32 v211, v211
	v_rcp_f32_e32 v212, v212
	v_rcp_f32_e32 v213, v213
	v_mul_f32_e32 v218, v148, v148
	v_mul_f32_e32 v219, v149, v149
	v_mul_f32_e32 v220, v150, v150
	v_mul_f32_e32 v221, v151, v151
	v_fmaak_f32 v214, v210, v134, 0xbf3a00e3
	v_fmaak_f32 v215, v211, v134, 0xbf3a00e3
	v_fmaak_f32 v216, v212, v134, 0xbf3a00e3
	v_fmaak_f32 v217, v213, v134, 0xbf3a00e3
	v_fmaak_f32 v214, v214, v210, 0x3f35f0e3
	v_fmaak_f32 v215, v215, v211, 0x3f35f0e3
	v_fmaak_f32 v216, v216, v212, 0x3f35f0e3
	v_fmaak_f32 v217, v217, v213, 0x3f35f0e3
	v_fmaak_f32 v214, v214, v210, 0xbe11a98e
	v_fmaak_f32 v215, v215, v211, 0xbe11a98e
	v_fmaak_f32 v216, v216, v212, 0xbe11a98e
	v_fmaak_f32 v217, v217, v213, 0xbe11a98e
	v_fmaak_f32 v214, v214, v210, 0x3e027906
	v_fmaak_f32 v215, v215, v211, 0x3e027906
	v_fmaak_f32 v216, v216, v212, 0x3e027906
	v_fmaak_f32 v217, v217, v213, 0x3e027906
	v_mul_f32_e32 v214, v214, v210
	v_mul_f32_e32 v215, v215, v211
	v_mul_f32_e32 v216, v216, v212
	v_mul_f32_e32 v217, v217, v213
	v_mul_f32_e32 v218, 0xbf38aa3b, v218
	v_mul_f32_e32 v219, 0xbf38aa3b, v219
	v_mul_f32_e32 v220, 0xbf38aa3b, v220
	v_mul_f32_e32 v221, 0xbf38aa3b, v221
	v_exp_f32_e32 v218, v218
	v_exp_f32_e32 v219, v219
	v_exp_f32_e32 v220, v220
	v_exp_f32_e32 v221, v221
	v_mul_f32_e32 v218, v218, v214
	v_mul_f32_e32 v219, v219, v215
	v_mul_f32_e32 v220, v220, v216
	v_mul_f32_e32 v221, v221, v217
	v_max_f32_e32 v210, 0, v148
	v_max_f32_e32 v211, 0, v149
	v_max_f32_e32 v212, 0, v150
	v_max_f32_e32 v213, 0, v151
	v_fma_f32 v222, -|v148|, v218, v210
	v_fma_f32 v223, -|v149|, v219, v211
	v_fma_f32 v224, -|v150|, v220, v212
	v_fma_f32 v225, -|v151|, v221, v213
	v_mul_f32_e32 v144, v144, v222
	v_mul_f32_e32 v145, v145, v223
	v_mul_f32_e32 v146, v146, v224
	v_mul_f32_e32 v147, v147, v225
	v_cvt_pk_bf16_f32 v154, v144, v145
	v_cvt_pk_bf16_f32 v155, v146, v147
	s_mov_b32 s14, 0xc6000
	v_lshl_add_u64 v[198:199], v[132:133], 0, s[14:15]
	v_permlane16_swap_b32_e32 v152, v154
	v_permlane16_swap_b32_e32 v153, v155
	global_store_dwordx4 v[198:199], v[152:155], off
	v_cndmask_b32_e64 v104, v12, v20, s[16:17]
	v_cndmask_b32_e64 v105, v13, v21, s[16:17]
	v_cndmask_b32_e64 v106, v14, v22, s[16:17]
	v_cndmask_b32_e64 v107, v15, v23, s[16:17]
	v_cndmask_b32_e64 v108, v12, v4, s[4:5]
	v_cndmask_b32_e64 v109, v13, v5, s[4:5]
	v_cndmask_b32_e64 v110, v14, v6, s[4:5]
	v_cndmask_b32_e64 v111, v15, v7, s[4:5]
	v_mul_f32_dpp v144, v104, v160 row_ror:1 row_mask:0xf bank_mask:0xf
	v_mul_f32_dpp v145, v105, v161 row_ror:1 row_mask:0xf bank_mask:0xf
	v_mul_f32_dpp v146, v106, v162 row_ror:1 row_mask:0xf bank_mask:0xf
	v_mul_f32_dpp v147, v107, v163 row_ror:1 row_mask:0xf bank_mask:0xf
	v_fmac_f32_e32 v144, v12, v164
	v_fmac_f32_e32 v145, v13, v165
	v_fmac_f32_e32 v146, v14, v166
	v_fmac_f32_e32 v147, v15, v167
	v_fmac_f32_dpp v144, v108, v168 row_ror:15 row_mask:0xf bank_mask:0xf
	v_fmac_f32_dpp v145, v109, v169 row_ror:15 row_mask:0xf bank_mask:0xf
	v_fmac_f32_dpp v146, v110, v170 row_ror:15 row_mask:0xf bank_mask:0xf
	v_fmac_f32_dpp v147, v111, v171 row_ror:15 row_mask:0xf bank_mask:0xf
	v_add_f32_e32 v144, v172, v144
	v_add_f32_e32 v145, v173, v145
	v_add_f32_e32 v146, v174, v146
	v_add_f32_e32 v147, v175, v147
	v_cndmask_b32_e64 v104, v8, v16, s[16:17]
	v_cndmask_b32_e64 v105, v9, v17, s[16:17]
	v_cndmask_b32_e64 v106, v10, v18, s[16:17]
	v_cndmask_b32_e64 v107, v11, v19, s[16:17]
	v_cndmask_b32_e64 v108, v8, v0, s[4:5]
	v_cndmask_b32_e64 v109, v9, v1, s[4:5]
	v_cndmask_b32_e64 v110, v10, v2, s[4:5]
	v_cndmask_b32_e64 v111, v11, v3, s[4:5]
	v_mul_f32_dpp v148, v104, v182 row_ror:1 row_mask:0xf bank_mask:0xf
	v_mul_f32_dpp v149, v105, v183 row_ror:1 row_mask:0xf bank_mask:0xf
	v_mul_f32_dpp v150, v106, v184 row_ror:1 row_mask:0xf bank_mask:0xf
	v_mul_f32_dpp v151, v107, v185 row_ror:1 row_mask:0xf bank_mask:0xf
	v_fmac_f32_e32 v148, v8, v186
	v_fmac_f32_e32 v149, v9, v187
	v_fmac_f32_e32 v150, v10, v188
	v_fmac_f32_e32 v151, v11, v189
	v_fmac_f32_dpp v148, v108, v190 row_ror:15 row_mask:0xf bank_mask:0xf
	v_fmac_f32_dpp v149, v109, v191 row_ror:15 row_mask:0xf bank_mask:0xf
	v_fmac_f32_dpp v150, v110, v192 row_ror:15 row_mask:0xf bank_mask:0xf
	v_fmac_f32_dpp v151, v111, v193 row_ror:15 row_mask:0xf bank_mask:0xf
	v_add_f32_e32 v148, v194, v148
	v_add_f32_e32 v149, v195, v149
	v_add_f32_e32 v150, v196, v150
	v_add_f32_e32 v151, v197, v151
	v_fma_f32 v210, |v148|, s10, 1.0
	v_fma_f32 v211, |v149|, s10, 1.0
	v_fma_f32 v212, |v150|, s10, 1.0
	v_fma_f32 v213, |v151|, s10, 1.0
	v_rcp_f32_e32 v210, v210
	v_rcp_f32_e32 v211, v211
	v_rcp_f32_e32 v212, v212
	v_rcp_f32_e32 v213, v213
	v_mul_f32_e32 v218, v148, v148
	v_mul_f32_e32 v219, v149, v149
	v_mul_f32_e32 v220, v150, v150
	v_mul_f32_e32 v221, v151, v151
	v_fmaak_f32 v214, v210, v134, 0xbf3a00e3
	v_fmaak_f32 v215, v211, v134, 0xbf3a00e3
	v_fmaak_f32 v216, v212, v134, 0xbf3a00e3
	v_fmaak_f32 v217, v213, v134, 0xbf3a00e3
	v_fmaak_f32 v214, v214, v210, 0x3f35f0e3
	v_fmaak_f32 v215, v215, v211, 0x3f35f0e3
	v_fmaak_f32 v216, v216, v212, 0x3f35f0e3
	v_fmaak_f32 v217, v217, v213, 0x3f35f0e3
	v_fmaak_f32 v214, v214, v210, 0xbe11a98e
	v_fmaak_f32 v215, v215, v211, 0xbe11a98e
	v_fmaak_f32 v216, v216, v212, 0xbe11a98e
	v_fmaak_f32 v217, v217, v213, 0xbe11a98e
	v_fmaak_f32 v214, v214, v210, 0x3e027906
	v_fmaak_f32 v215, v215, v211, 0x3e027906
	v_fmaak_f32 v216, v216, v212, 0x3e027906
	v_fmaak_f32 v217, v217, v213, 0x3e027906
	v_mul_f32_e32 v214, v214, v210
	v_mul_f32_e32 v215, v215, v211
	v_mul_f32_e32 v216, v216, v212
	v_mul_f32_e32 v217, v217, v213
	v_mul_f32_e32 v218, 0xbf38aa3b, v218
	v_mul_f32_e32 v219, 0xbf38aa3b, v219
	v_mul_f32_e32 v220, 0xbf38aa3b, v220
	v_mul_f32_e32 v221, 0xbf38aa3b, v221
	v_exp_f32_e32 v218, v218
	v_exp_f32_e32 v219, v219
	v_exp_f32_e32 v220, v220
	v_exp_f32_e32 v221, v221
	v_mul_f32_e32 v218, v218, v214
	v_mul_f32_e32 v219, v219, v215
	v_mul_f32_e32 v220, v220, v216
	v_mul_f32_e32 v221, v221, v217
	v_max_f32_e32 v210, 0, v148
	v_max_f32_e32 v211, 0, v149
	v_max_f32_e32 v212, 0, v150
	v_max_f32_e32 v213, 0, v151
	v_fma_f32 v222, -|v148|, v218, v210
	v_fma_f32 v223, -|v149|, v219, v211
	v_fma_f32 v224, -|v150|, v220, v212
	v_fma_f32 v225, -|v151|, v221, v213
	v_mul_f32_e32 v144, v144, v222
	v_mul_f32_e32 v145, v145, v223
	v_mul_f32_e32 v146, v146, v224
	v_mul_f32_e32 v147, v147, v225
	v_cvt_pk_bf16_f32 v142, v144, v145
	v_cvt_pk_bf16_f32 v143, v146, v147
	s_mov_b32 s14, 0xdc000
	v_lshl_add_u64 v[198:199], v[132:133], 0, s[14:15]
	v_permlane16_swap_b32_e32 v140, v142
	v_permlane16_swap_b32_e32 v141, v143
	global_store_dwordx4 v[198:199], v[140:143], off
	s_waitcnt lgkmcnt(0)
	v_cndmask_b32_e64 v104, v4, v12, s[16:17]
	v_cndmask_b32_e64 v105, v5, v13, s[16:17]
	v_cndmask_b32_e64 v106, v6, v14, s[16:17]
	v_cndmask_b32_e64 v107, v7, v15, s[16:17]
	v_cndmask_b32_e64 v108, v4, v120, s[4:5]
	v_cndmask_b32_e64 v109, v5, v121, s[4:5]
	v_cndmask_b32_e64 v110, v6, v122, s[4:5]
	v_cndmask_b32_e64 v111, v7, v123, s[4:5]
	v_mul_f32_dpp v144, v104, v160 row_ror:1 row_mask:0xf bank_mask:0xf
	v_mul_f32_dpp v145, v105, v161 row_ror:1 row_mask:0xf bank_mask:0xf
	v_mul_f32_dpp v146, v106, v162 row_ror:1 row_mask:0xf bank_mask:0xf
	v_mul_f32_dpp v147, v107, v163 row_ror:1 row_mask:0xf bank_mask:0xf
	v_fmac_f32_e32 v144, v4, v164
	v_fmac_f32_e32 v145, v5, v165
	v_fmac_f32_e32 v146, v6, v166
	v_fmac_f32_e32 v147, v7, v167
	v_fmac_f32_dpp v144, v108, v168 row_ror:15 row_mask:0xf bank_mask:0xf
	v_fmac_f32_dpp v145, v109, v169 row_ror:15 row_mask:0xf bank_mask:0xf
	v_fmac_f32_dpp v146, v110, v170 row_ror:15 row_mask:0xf bank_mask:0xf
	v_fmac_f32_dpp v147, v111, v171 row_ror:15 row_mask:0xf bank_mask:0xf
	v_add_f32_e32 v144, v172, v144
	v_add_f32_e32 v145, v173, v145
	v_add_f32_e32 v146, v174, v146
	v_add_f32_e32 v147, v175, v147
	v_cndmask_b32_e64 v104, v0, v8, s[16:17]
	v_cndmask_b32_e64 v105, v1, v9, s[16:17]
	v_cndmask_b32_e64 v106, v2, v10, s[16:17]
	v_cndmask_b32_e64 v107, v3, v11, s[16:17]
	v_cndmask_b32_e64 v108, v0, v124, s[4:5]
	v_cndmask_b32_e64 v109, v1, v125, s[4:5]
	v_cndmask_b32_e64 v110, v2, v126, s[4:5]
	v_cndmask_b32_e64 v111, v3, v127, s[4:5]
	v_mul_f32_dpp v148, v104, v182 row_ror:1 row_mask:0xf bank_mask:0xf
	v_mul_f32_dpp v149, v105, v183 row_ror:1 row_mask:0xf bank_mask:0xf
	v_mul_f32_dpp v150, v106, v184 row_ror:1 row_mask:0xf bank_mask:0xf
	v_mul_f32_dpp v151, v107, v185 row_ror:1 row_mask:0xf bank_mask:0xf
	v_fmac_f32_e32 v148, v0, v186
	v_fmac_f32_e32 v149, v1, v187
	v_fmac_f32_e32 v150, v2, v188
	v_fmac_f32_e32 v151, v3, v189
	v_fmac_f32_dpp v148, v108, v190 row_ror:15 row_mask:0xf bank_mask:0xf
	v_fmac_f32_dpp v149, v109, v191 row_ror:15 row_mask:0xf bank_mask:0xf
	v_fmac_f32_dpp v150, v110, v192 row_ror:15 row_mask:0xf bank_mask:0xf
	v_fmac_f32_dpp v151, v111, v193 row_ror:15 row_mask:0xf bank_mask:0xf
	v_add_f32_e32 v148, v194, v148
	v_add_f32_e32 v149, v195, v149
	v_add_f32_e32 v150, v196, v150
	v_add_f32_e32 v151, v197, v151
	v_fma_f32 v210, |v148|, s10, 1.0
	v_fma_f32 v211, |v149|, s10, 1.0
	v_fma_f32 v212, |v150|, s10, 1.0
	v_fma_f32 v213, |v151|, s10, 1.0
	v_rcp_f32_e32 v210, v210
	v_rcp_f32_e32 v211, v211
	v_rcp_f32_e32 v212, v212
	v_rcp_f32_e32 v213, v213
	v_mul_f32_e32 v218, v148, v148
	v_mul_f32_e32 v219, v149, v149
	v_mul_f32_e32 v220, v150, v150
	v_mul_f32_e32 v221, v151, v151
	v_fmaak_f32 v214, v210, v134, 0xbf3a00e3
	v_fmaak_f32 v215, v211, v134, 0xbf3a00e3
	v_fmaak_f32 v216, v212, v134, 0xbf3a00e3
	v_fmaak_f32 v217, v213, v134, 0xbf3a00e3
	v_fmaak_f32 v214, v214, v210, 0x3f35f0e3
	v_fmaak_f32 v215, v215, v211, 0x3f35f0e3
	v_fmaak_f32 v216, v216, v212, 0x3f35f0e3
	v_fmaak_f32 v217, v217, v213, 0x3f35f0e3
	v_fmaak_f32 v214, v214, v210, 0xbe11a98e
	v_fmaak_f32 v215, v215, v211, 0xbe11a98e
	v_fmaak_f32 v216, v216, v212, 0xbe11a98e
	v_fmaak_f32 v217, v217, v213, 0xbe11a98e
	v_fmaak_f32 v214, v214, v210, 0x3e027906
	v_fmaak_f32 v215, v215, v211, 0x3e027906
	v_fmaak_f32 v216, v216, v212, 0x3e027906
	v_fmaak_f32 v217, v217, v213, 0x3e027906
	v_mul_f32_e32 v214, v214, v210
	v_mul_f32_e32 v215, v215, v211
	v_mul_f32_e32 v216, v216, v212
	v_mul_f32_e32 v217, v217, v213
	v_mul_f32_e32 v218, 0xbf38aa3b, v218
	v_mul_f32_e32 v219, 0xbf38aa3b, v219
	v_mul_f32_e32 v220, 0xbf38aa3b, v220
	v_mul_f32_e32 v221, 0xbf38aa3b, v221
	v_exp_f32_e32 v218, v218
	v_exp_f32_e32 v219, v219
	v_exp_f32_e32 v220, v220
	v_exp_f32_e32 v221, v221
	v_mul_f32_e32 v218, v218, v214
	v_mul_f32_e32 v219, v219, v215
	v_mul_f32_e32 v220, v220, v216
	v_mul_f32_e32 v221, v221, v217
	v_max_f32_e32 v210, 0, v148
	v_max_f32_e32 v211, 0, v149
	v_max_f32_e32 v212, 0, v150
	v_max_f32_e32 v213, 0, v151
	v_fma_f32 v222, -|v148|, v218, v210
	v_fma_f32 v223, -|v149|, v219, v211
	v_fma_f32 v224, -|v150|, v220, v212
	v_fma_f32 v225, -|v151|, v221, v213
	v_mul_f32_e32 v144, v144, v222
	v_mul_f32_e32 v145, v145, v223
	v_mul_f32_e32 v146, v146, v224
	v_mul_f32_e32 v147, v147, v225
	v_cvt_pk_bf16_f32 v138, v144, v145
	v_cvt_pk_bf16_f32 v139, v146, v147
	s_mov_b32 s14, 0xf2000
	v_lshl_add_u64 v[198:199], v[132:133], 0, s[14:15]
	v_permlane16_swap_b32_e32 v136, v138
	v_permlane16_swap_b32_e32 v137, v139
	s_and_b64 s[18:19], s[16:17], s[6:7]
	s_andn2_b64 s[18:19], exec, s[18:19]
	s_and_saveexec_b64 s[20:21], s[18:19]
	global_store_dwordx4 v[198:199], v[136:139], off
	s_mov_b64 exec, s[20:21]
	s_andn2_b64 vcc, exec, s[42:43]
	s_mov_b64 s[0:1], -1
	s_cbranch_vccnz .LBB0_883
	s_branch .LBB0_1029

.LBB0_1168:
	s_add_u32 s44, s18, 0x100
	v_mov_b32_e32 v0, 0
	s_addc_u32 s45, s19, 0
	s_mov_b32 s46, -2
	v_mov_b32_e32 v1, v0
	v_mov_b32_e32 v2, v0
	v_mov_b32_e32 v3, v0
	v_mov_b32_e32 v4, v0
	v_mov_b32_e32 v5, v0
	v_mov_b32_e32 v6, v0
	v_mov_b32_e32 v7, v0
	v_mov_b32_e32 v8, v0
	v_mov_b32_e32 v9, v0
	v_mov_b32_e32 v10, v0
	v_mov_b32_e32 v11, v0
	v_mov_b32_e32 v16, v0
	v_mov_b32_e32 v17, v0
	v_mov_b32_e32 v18, v0
	v_mov_b32_e32 v19, v0
	v_mov_b32_e32 v24, v0
	v_mov_b32_e32 v25, v0
	v_mov_b32_e32 v26, v0
	v_mov_b32_e32 v27, v0
	v_mov_b32_e32 v32, v0
	v_mov_b32_e32 v33, v0
	v_mov_b32_e32 v34, v0
	v_mov_b32_e32 v35, v0
	v_mov_b32_e32 v40, v0
	v_mov_b32_e32 v41, v0
	v_mov_b32_e32 v42, v0
	v_mov_b32_e32 v43, v0
	v_mov_b32_e32 v48, v0
	v_mov_b32_e32 v49, v0
	v_mov_b32_e32 v50, v0
	v_mov_b32_e32 v51, v0
	v_mov_b32_e32 v12, v0
	v_mov_b32_e32 v13, v0
	v_mov_b32_e32 v14, v0
	v_mov_b32_e32 v15, v0
	v_mov_b32_e32 v20, v0
	v_mov_b32_e32 v21, v0
	v_mov_b32_e32 v22, v0
	v_mov_b32_e32 v23, v0
	v_mov_b32_e32 v28, v0
	v_mov_b32_e32 v29, v0
	v_mov_b32_e32 v30, v0
	v_mov_b32_e32 v31, v0
	v_mov_b32_e32 v36, v0
	v_mov_b32_e32 v37, v0
	v_mov_b32_e32 v38, v0
	v_mov_b32_e32 v39, v0
	v_mov_b32_e32 v44, v0
	v_mov_b32_e32 v45, v0
	v_mov_b32_e32 v46, v0
	v_mov_b32_e32 v47, v0
	v_mov_b32_e32 v52, v0
	v_mov_b32_e32 v53, v0
	v_mov_b32_e32 v54, v0
	v_mov_b32_e32 v55, v0
	v_mov_b32_e32 v56, v0
	v_mov_b32_e32 v57, v0
	v_mov_b32_e32 v58, v0
	v_mov_b32_e32 v59, v0
	v_mov_b32_e32 v60, v0
	v_mov_b32_e32 v61, v0
	v_mov_b32_e32 v62, v0
	v_mov_b32_e32 v63, v0
	s_waitcnt vmcnt(0)
	v_mov_b32_e32 v64, v0
	v_mov_b32_e32 v65, v0
	v_mov_b32_e32 v66, v0
	v_mov_b32_e32 v67, v0
	v_mov_b32_e32 v68, v0
	v_mov_b32_e32 v69, v0
	v_mov_b32_e32 v70, v0
	v_mov_b32_e32 v71, v0
	v_mov_b32_e32 v72, v0
	v_mov_b32_e32 v73, v0
	v_mov_b32_e32 v74, v0
	v_mov_b32_e32 v75, v0
	v_mov_b32_e32 v80, v0
	v_mov_b32_e32 v81, v0
	v_mov_b32_e32 v82, v0
	v_mov_b32_e32 v83, v0
	v_mov_b32_e32 v88, v0
	v_mov_b32_e32 v89, v0
	v_mov_b32_e32 v90, v0
	v_mov_b32_e32 v91, v0
	v_mov_b32_e32 v100, v0
	v_mov_b32_e32 v101, v0
	v_mov_b32_e32 v102, v0
	v_mov_b32_e32 v103, v0
	v_mov_b32_e32 v108, v0
	v_mov_b32_e32 v109, v0
	v_mov_b32_e32 v110, v0
	v_mov_b32_e32 v111, v0
	v_mov_b32_e32 v116, v0
	v_mov_b32_e32 v117, v0
	v_mov_b32_e32 v118, v0
	v_mov_b32_e32 v119, v0
	v_mov_b32_e32 v76, v0
	v_mov_b32_e32 v77, v0
	v_mov_b32_e32 v78, v0
	v_mov_b32_e32 v79, v0
	v_mov_b32_e32 v84, v0
	v_mov_b32_e32 v85, v0
	v_mov_b32_e32 v86, v0
	v_mov_b32_e32 v87, v0
	v_mov_b32_e32 v92, v0
	v_mov_b32_e32 v93, v0
	v_mov_b32_e32 v94, v0
	v_mov_b32_e32 v95, v0
	v_mov_b32_e32 v96, v0
	v_mov_b32_e32 v97, v0
	v_mov_b32_e32 v98, v0
	v_mov_b32_e32 v99, v0
	v_mov_b32_e32 v104, v0
	v_mov_b32_e32 v105, v0
	v_mov_b32_e32 v106, v0
	v_mov_b32_e32 v107, v0
	v_mov_b32_e32 v112, v0
	v_mov_b32_e32 v113, v0
	v_mov_b32_e32 v114, v0
	v_mov_b32_e32 v115, v0
	v_mov_b32_e32 v120, v0
	v_mov_b32_e32 v121, v0
	v_mov_b32_e32 v122, v0
	v_mov_b32_e32 v123, v0
	v_mov_b32_e32 v124, v0
	v_mov_b32_e32 v125, v0
	v_mov_b32_e32 v126, v0
	v_mov_b32_e32 v127, v0
	s_nop 0
	s_nop 0
	s_nop 0
	s_nop 0
	s_nop 0
	s_nop 0
	s_nop 0
	s_nop 0
	s_nop 0
	s_nop 0
	s_nop 0
	s_nop 0
	s_nop 0
	s_nop 0

.LBB0_1194:
	s_add_u32 s43, s16, 0x100
	v_mov_b32_e32 v0, 0
	s_addc_u32 s44, s17, 0
	s_mov_b32 s45, -2
	v_mov_b32_e32 v1, v0
	v_mov_b32_e32 v2, v0
	v_mov_b32_e32 v3, v0
	v_mov_b32_e32 v4, v0
	v_mov_b32_e32 v5, v0
	v_mov_b32_e32 v6, v0
	v_mov_b32_e32 v7, v0
	v_mov_b32_e32 v16, v0
	v_mov_b32_e32 v17, v0
	v_mov_b32_e32 v18, v0
	v_mov_b32_e32 v19, v0
	v_mov_b32_e32 v20, v0
	v_mov_b32_e32 v21, v0
	v_mov_b32_e32 v22, v0
	v_mov_b32_e32 v23, v0
	v_mov_b32_e32 v32, v0
	v_mov_b32_e32 v33, v0
	v_mov_b32_e32 v34, v0
	v_mov_b32_e32 v35, v0
	v_mov_b32_e32 v36, v0
	v_mov_b32_e32 v37, v0
	v_mov_b32_e32 v38, v0
	v_mov_b32_e32 v39, v0
	v_mov_b32_e32 v48, v0
	v_mov_b32_e32 v49, v0
	v_mov_b32_e32 v50, v0
	v_mov_b32_e32 v51, v0
	v_mov_b32_e32 v52, v0
	v_mov_b32_e32 v53, v0
	v_mov_b32_e32 v54, v0
	v_mov_b32_e32 v55, v0
	v_mov_b32_e32 v8, v0
	v_mov_b32_e32 v9, v0
	v_mov_b32_e32 v10, v0
	v_mov_b32_e32 v11, v0
	v_mov_b32_e32 v12, v0
	v_mov_b32_e32 v13, v0
	v_mov_b32_e32 v14, v0
	v_mov_b32_e32 v15, v0
	v_mov_b32_e32 v24, v0
	v_mov_b32_e32 v25, v0
	v_mov_b32_e32 v26, v0
	v_mov_b32_e32 v27, v0
	v_mov_b32_e32 v28, v0
	v_mov_b32_e32 v29, v0
	v_mov_b32_e32 v30, v0
	v_mov_b32_e32 v31, v0
	v_mov_b32_e32 v40, v0
	v_mov_b32_e32 v41, v0
	v_mov_b32_e32 v42, v0
	v_mov_b32_e32 v43, v0
	v_mov_b32_e32 v44, v0
	v_mov_b32_e32 v45, v0
	v_mov_b32_e32 v46, v0
	v_mov_b32_e32 v47, v0
	v_mov_b32_e32 v56, v0
	v_mov_b32_e32 v57, v0
	v_mov_b32_e32 v58, v0
	v_mov_b32_e32 v59, v0
	v_mov_b32_e32 v60, v0
	v_mov_b32_e32 v61, v0
	v_mov_b32_e32 v62, v0
	v_mov_b32_e32 v63, v0
	s_waitcnt vmcnt(0)
	v_mov_b32_e32 v64, v0
	v_mov_b32_e32 v65, v0
	v_mov_b32_e32 v66, v0
	v_mov_b32_e32 v67, v0
	v_mov_b32_e32 v68, v0
	v_mov_b32_e32 v69, v0
	v_mov_b32_e32 v70, v0
	v_mov_b32_e32 v71, v0
	v_mov_b32_e32 v80, v0
	v_mov_b32_e32 v81, v0
	v_mov_b32_e32 v82, v0
	v_mov_b32_e32 v83, v0
	v_mov_b32_e32 v84, v0
	v_mov_b32_e32 v85, v0
	v_mov_b32_e32 v86, v0
	v_mov_b32_e32 v87, v0
	v_mov_b32_e32 v96, v0
	v_mov_b32_e32 v97, v0
	v_mov_b32_e32 v98, v0
	v_mov_b32_e32 v99, v0
	v_mov_b32_e32 v100, v0
	v_mov_b32_e32 v101, v0
	v_mov_b32_e32 v102, v0
	v_mov_b32_e32 v103, v0
	v_mov_b32_e32 v112, v0
	v_mov_b32_e32 v113, v0
	v_mov_b32_e32 v114, v0
	v_mov_b32_e32 v115, v0
	v_mov_b32_e32 v116, v0
	v_mov_b32_e32 v117, v0
	v_mov_b32_e32 v118, v0
	v_mov_b32_e32 v119, v0
	v_mov_b32_e32 v72, v0
	v_mov_b32_e32 v73, v0
	v_mov_b32_e32 v74, v0
	v_mov_b32_e32 v75, v0
	v_mov_b32_e32 v76, v0
	v_mov_b32_e32 v77, v0
	v_mov_b32_e32 v78, v0
	v_mov_b32_e32 v79, v0
	v_mov_b32_e32 v88, v0
	v_mov_b32_e32 v89, v0
	v_mov_b32_e32 v90, v0
	v_mov_b32_e32 v91, v0
	v_mov_b32_e32 v92, v0
	v_mov_b32_e32 v93, v0
	v_mov_b32_e32 v94, v0
	v_mov_b32_e32 v95, v0
	v_mov_b32_e32 v104, v0
	v_mov_b32_e32 v105, v0
	v_mov_b32_e32 v106, v0
	v_mov_b32_e32 v107, v0
	v_mov_b32_e32 v108, v0
	v_mov_b32_e32 v109, v0
	v_mov_b32_e32 v110, v0
	v_mov_b32_e32 v111, v0
	v_mov_b32_e32 v120, v0
	v_mov_b32_e32 v121, v0
	v_mov_b32_e32 v122, v0
	v_mov_b32_e32 v123, v0
	v_mov_b32_e32 v124, v0
	v_mov_b32_e32 v125, v0
	v_mov_b32_e32 v126, v0
	v_mov_b32_e32 v127, v0
	s_nop 0
	s_nop 0
